# scan loops: packed fp32 VOP3P ops (v_pk_mul/add/fma_f32) split into scalar pairs, bit-identical
# speedup vs baseline: 1.0014x; 1.0014x over previous
.LBB0_507:
	s_or_b64 exec, exec, s[16:17]
	s_waitcnt lgkmcnt(0)
	s_barrier
	ds_read_b128 v[52:55], v100
	ds_read_b128 v[56:59], v101 offset:36864
	ds_read_b128 v[60:63], v100 offset:64
	ds_read_b128 v[64:67], v101 offset:36928
	ds_read_b128 v[68:71], v101 offset:39168
	ds_read_b128 v[72:75], v101 offset:39232
	ds_read_b128 v[76:79], v101 offset:41472
	ds_read_b128 v[86:89], v101 offset:41536
	s_waitcnt lgkmcnt(6)
	v_mfma_f32_16x16x32_f16 v[56:59], v[52:55], v[56:59], 0
	ds_read_b128 v[90:93], v101 offset:43776
	ds_read_b128 v[158:161], v101 offset:43840
	ds_read_b128 v[166:169], v101 offset:27648
	ds_read_b128 v[170:173], v101 offset:32256
	s_mov_b32 s0, 0x358637bd
	s_waitcnt lgkmcnt(7)
	v_mfma_f32_16x16x32_f16 v[68:71], v[52:55], v[68:71], 0
	s_mov_b32 s4, 0x3c800000
	s_waitcnt lgkmcnt(5)
	v_mfma_f32_16x16x32_f16 v[76:79], v[52:55], v[76:79], 0
	s_waitcnt lgkmcnt(3)
	v_mfma_f32_16x16x32_f16 v[162:165], v[52:55], v[90:93], 0
	v_mfma_f32_16x16x32_f16 v[52:55], v[60:63], v[64:67], v[56:59]
	v_mfma_f32_16x16x32_f16 v[56:59], v[60:63], v[72:75], v[68:71]
	s_nop 2
	ds_read_b128 v[68:71], v101 offset:34560
	ds_read_b128 v[174:177], v100 offset:9216
	ds_read_b128 v[178:181], v100 offset:9280
	v_mfma_f32_16x16x32_f16 v[64:67], v[60:63], v[86:89], v[76:79]
	ds_read_b128 v[88:91], v140 offset:46848
	ds_read_b128 v[92:95], v140 offset:47104
	ds_read_b128 v[72:75], v140 offset:46592
	ds_read_b128 v[96:99], v140 offset:46336
	s_waitcnt vmcnt(13)
	v_cvt_f32_f16_e32 v86, v80
	s_waitcnt lgkmcnt(3)
	v_max_f32_e32 v82, v88, v88
	v_mfma_f32_16x16x32_f16 v[76:79], v[60:63], v[158:161], v[162:165]
	ds_read_b128 v[60:63], v101 offset:27712
	ds_read_b128 v[158:161], v101 offset:29952
	s_nop 0
	ds_read_b128 v[162:165], v101 offset:30016
	s_waitcnt lgkmcnt(3)
	v_fma_f32 v81, v72, v96, v92
	v_max_f32_e64 v88, |v81|, v82
	v_div_scale_f32 v81, s[16:17], v88, v88, 1.0
	v_rcp_f32_e32 v82, v81
	v_mfma_f32_16x16x32_f16 v[166:169], v[174:177], v[166:169], 0
	v_cvt_f32_f16_e32 v96, v84
	ds_read_b128 v[210:213], v101 offset:32320
	ds_read_b128 v[214:217], v101 offset:34624
	v_fma_f32 v83, -v81, v82, 1.0
	s_waitcnt lgkmcnt(3)
	v_mfma_f32_16x16x32_f16 v[158:161], v[174:177], v[158:161], 0
	v_fmac_f32_e32 v82, v83, v82
	v_fmac_f32_e32 v95, v75, v99
	v_mfma_f32_16x16x32_f16 v[170:173], v[174:177], v[170:173], 0
	v_mfma_f32_16x16x32_f16 v[174:177], v[174:177], v[68:71], 0
	v_div_scale_f32 v68, vcc, 1.0, v88, 1.0
	v_mul_f32_e32 v83, v68, v82
	v_fma_f32 v69, -v81, v83, v68
	v_fmac_f32_e32 v83, v69, v82
	v_fma_f32 v81, -v81, v83, v68
	s_waitcnt lgkmcnt(2)
	v_mfma_f32_16x16x32_f16 v[68:71], v[178:181], v[162:165], v[158:161]
	v_div_fmas_f32 v92, v81, v82, v83
	v_div_fixup_f32 v88, v92, v88, 1.0
	v_mul_f32_e32 v92, 0xbfb8aa3b, v96
	s_waitcnt vmcnt(12)
	v_cvt_f32_f16_e32 v158, v85
	v_mul_f32_e32 v159, 0xbfb8aa3b, v86
	v_exp_f32_e32 v159, v159
	v_cvt_f32_f16_e32 v96, v157
	v_mul_f32_e32 v158, 0xbfb8aa3b, v158
	v_exp_f32_e32 v158, v158
	v_exp_f32_e32 v160, v92
	v_mul_f32_e32 v92, 0xbfb8aa3b, v96
	v_exp_f32_e32 v161, v92
	v_add_f32_e64 v158, v158, 1.0
	v_add_f32_e64 v159, v159, 1.0
	s_waitcnt lgkmcnt(1)
	v_mfma_f32_16x16x32_f16 v[80:83], v[178:181], v[210:213], v[170:173]
	v_div_scale_f32 v157, s[16:17], v159, v159, 1.0
	v_rcp_f32_e32 v162, v157
	v_add_f32_e64 v160, v160, 1.0
	v_add_f32_e64 v161, v161, 1.0
	s_waitcnt lgkmcnt(0)
	v_mfma_f32_16x16x32_f16 v[84:87], v[178:181], v[214:217], v[174:177]
	s_nop 2
	v_mov_b32_e32 v165, v80
	v_fma_f32 v92, -v157, v162, 1.0
	v_fmac_f32_e32 v162, v92, v162
	v_div_scale_f32 v92, vcc, 1.0, v159, 1.0
	v_mul_f32_e32 v96, v92, v162
	v_fma_f32 v163, -v157, v96, v92
	v_fmac_f32_e32 v96, v163, v162
	v_fma_f32 v92, -v157, v96, v92
	v_div_scale_f32 v157, s[16:17], v158, v158, 1.0
	v_rcp_f32_e32 v163, v157
	v_div_fmas_f32 v92, v92, v162, v96
	v_div_fixup_f32 v159, v92, v159, 1.0
	v_mov_b32_e32 v164, v84
	v_fma_f32 v92, -v157, v163, 1.0
	v_fmac_f32_e32 v163, v92, v163
	v_div_scale_f32 v92, vcc, 1.0, v158, 1.0
	v_mul_f32_e32 v96, v92, v163
	v_fma_f32 v162, -v157, v96, v92
	v_fmac_f32_e32 v96, v162, v163
	v_fma_f32 v92, -v157, v96, v92
	v_div_fmas_f32 v92, v92, v163, v96
	v_mov_b32_e32 v163, v64
	v_div_scale_f32 v64, s[16:17], v161, v161, 1.0
	v_mov_b32_e32 v162, v76
	v_rcp_f32_e32 v76, v64
	v_div_fixup_f32 v158, v92, v158, 1.0
	v_mfma_f32_16x16x32_f16 v[60:63], v[178:181], v[60:63], v[166:169]
	v_fma_f32 v162, v162, v72, v164
	v_fma_f32 v163, v163, v72, v165
	v_fma_f32 v80, -v64, v76, 1.0
	v_fmac_f32_e32 v76, v80, v76
	v_div_scale_f32 v80, vcc, 1.0, v161, 1.0
	v_mul_f32_e32 v84, v80, v76
	v_fma_f32 v92, -v64, v84, v80
	v_fmac_f32_e32 v84, v92, v76
	v_fma_f32 v64, -v64, v84, v80
	v_div_scale_f32 v80, s[16:17], v160, v160, 1.0
	v_rcp_f32_e32 v92, v80
	v_div_fmas_f32 v64, v64, v76, v84
	v_div_fixup_f32 v161, v64, v161, 1.0
	v_mov_b32_e32 v166, v52
	v_fma_f32 v64, -v80, v92, 1.0
	v_fmac_f32_e32 v92, v64, v92
	v_div_scale_f32 v64, vcc, 1.0, v160, 1.0
	v_mul_f32_e32 v76, v64, v92
	v_fma_f32 v84, -v80, v76, v64
	v_fmac_f32_e32 v76, v84, v92
	v_fma_f32 v64, -v80, v76, v64
	v_mov_b32_e32 v167, v56
	v_mov_b32_e32 v168, v60
	v_mov_b32_e32 v169, v68
	v_div_fmas_f32 v64, v64, v92, v76
	v_fma_f32 v166, v166, v72, v168
	v_fma_f32 v167, v167, v72, v169
	v_div_fixup_f32 v160, v64, v160, 1.0
	v_mul_f32_e64 v166, v166, v88
	v_mul_f32_e64 v167, v167, v88
	v_mul_f32_e64 v162, v162, v88
	v_mul_f32_e64 v163, v163, v88
	v_mul_f32_e64 v168, v160, v166
	v_mul_f32_e64 v169, v161, v167
	v_mul_f32_e64 v164, v158, v162
	v_mul_f32_e64 v165, v159, v163
	v_add_f32_e32 v52, 0, v168
	v_add_f32_e32 v52, v169, v52
	v_add_f32_e32 v52, v165, v52
	v_add_f32_e32 v52, v164, v52
	v_max_f32_e32 v56, v89, v89
	global_load_dword v89, v[102:103], off
	global_load_dword v88, v[102:103], off offset:64
	global_load_dword v84, v[102:103], off offset:128
	global_load_dword v76, v[102:103], off offset:192
	v_add_f32_dpp v52, v52, v52 quad_perm:[1,0,3,2] row_mask:0xf bank_mask:0xf bound_ctrl:1
	s_nop 1
	v_add_f32_dpp v52, v52, v52 quad_perm:[2,3,0,1] row_mask:0xf bank_mask:0xf bound_ctrl:1
	s_nop 1
	v_add_f32_dpp v52, v52, v52 row_ror:4 row_mask:0xf bank_mask:0xf bound_ctrl:1
	s_nop 1
	v_add_f32_dpp v52, v52, v52 row_ror:8 row_mask:0xf bank_mask:0xf bound_ctrl:1
	v_mul_f32_e32 v52, 0x3c800000, v52
	v_fma_f32 v160, v160, v166, -v52
	v_fma_f32 v161, v161, v167, -v52
	v_fma_f32 v158, v158, v162, -v52
	v_fma_f32 v159, v159, v163, -v52
	v_fma_f32 v52, v73, v97, v93
	v_max_f32_e64 v52, |v52|, v56
	v_div_scale_f32 v56, s[16:17], v52, v52, 1.0
	v_rcp_f32_e32 v60, v56
	v_mul_f32_e64 v164, v160, v160
	v_mul_f32_e64 v165, v161, v161
	v_mul_f32_e64 v162, v158, v158
	v_mul_f32_e64 v163, v159, v159
	v_fma_f32 v64, -v56, v60, 1.0
	v_fmac_f32_e32 v60, v64, v60
	v_div_scale_f32 v64, vcc, 1.0, v52, 1.0
	v_mul_f32_e32 v68, v64, v60
	v_fma_f32 v80, -v56, v68, v64
	v_fmac_f32_e32 v68, v80, v60
	v_fma_f32 v56, -v56, v68, v64
	s_waitcnt vmcnt(13)
	v_cvt_f32_f16_e32 v64, v156
	v_div_fmas_f32 v56, v56, v60, v68
	s_waitcnt vmcnt(12)
	v_cvt_f32_f16_e32 v60, v155
	v_cvt_f32_f16_e32 v68, v154
	v_mul_f32_e32 v64, 0xbfb8aa3b, v64
	v_exp_f32_e32 v93, v64
	v_mul_f32_e32 v60, 0xbfb8aa3b, v60
	v_exp_f32_e32 v92, v60
	v_cvt_f32_f16_e32 v60, v153
	v_div_fixup_f32 v52, v56, v52, 1.0
	v_mul_f32_e32 v56, 0xbfb8aa3b, v68
	v_add_f32_e64 v92, v92, 1.0
	v_add_f32_e64 v93, v93, 1.0
	v_exp_f32_e32 v96, v56
	v_div_scale_f32 v64, s[16:17], v93, v93, 1.0
	v_rcp_f32_e32 v68, v64
	v_mul_f32_e32 v56, 0xbfb8aa3b, v60
	v_exp_f32_e32 v97, v56
	v_mov_b32_e32 v153, v70
	v_fma_f32 v56, -v64, v68, 1.0
	v_fmac_f32_e32 v68, v56, v68
	v_div_scale_f32 v56, vcc, 1.0, v93, 1.0
	v_mul_f32_e32 v60, v56, v68
	v_fma_f32 v80, -v64, v60, v56
	v_fmac_f32_e32 v60, v80, v68
	v_fma_f32 v56, -v64, v60, v56
	v_div_scale_f32 v64, s[16:17], v92, v92, 1.0
	v_rcp_f32_e32 v80, v64
	v_div_fmas_f32 v56, v56, v68, v60
	v_div_fixup_f32 v93, v56, v93, 1.0
	v_add_f32_e64 v96, v96, 1.0
	v_add_f32_e64 v97, v97, 1.0
	v_fma_f32 v56, -v64, v80, 1.0
	v_fmac_f32_e32 v80, v56, v80
	v_div_scale_f32 v56, vcc, 1.0, v92, 1.0
	v_mul_f32_e32 v60, v56, v80
	v_fma_f32 v68, -v64, v60, v56
	v_fmac_f32_e32 v60, v68, v80
	v_fma_f32 v56, -v64, v60, v56
	v_div_fmas_f32 v56, v56, v80, v60
	v_div_fixup_f32 v92, v56, v92, 1.0
	v_div_scale_f32 v56, s[16:17], v97, v97, 1.0
	v_rcp_f32_e32 v60, v56
	v_mov_b32_e32 v64, v77
	v_mov_b32_e32 v80, v85
	v_fma_f32 v64, v64, v73, v80
	v_fma_f32 v65, v65, v73, v81
	v_fma_f32 v68, -v56, v60, 1.0
	v_fmac_f32_e32 v60, v68, v60
	v_div_scale_f32 v68, vcc, 1.0, v97, 1.0
	v_mul_f32_e32 v77, v68, v60
	v_fma_f32 v85, -v56, v77, v68
	v_fmac_f32_e32 v77, v85, v60
	v_fma_f32 v56, -v56, v77, v68
	v_div_scale_f32 v68, s[16:17], v96, v96, 1.0
	v_rcp_f32_e32 v85, v68
	v_div_fmas_f32 v56, v56, v60, v77
	v_div_fixup_f32 v97, v56, v97, 1.0
	v_mul_f32_e64 v64, v64, v52
	v_mul_f32_e64 v65, v65, v52
	v_fma_f32 v56, -v68, v85, 1.0
	v_fmac_f32_e32 v85, v56, v85
	v_div_scale_f32 v56, vcc, 1.0, v96, 1.0
	v_mul_f32_e32 v60, v56, v85
	v_fma_f32 v77, -v68, v60, v56
	v_fmac_f32_e32 v60, v77, v85
	v_fma_f32 v56, -v68, v60, v56
	v_div_fmas_f32 v56, v56, v85, v60
	v_div_fixup_f32 v96, v56, v96, 1.0
	v_mov_b32_e32 v56, v53
	v_mov_b32_e32 v68, v61
	v_fma_f32 v56, v56, v73, v68
	v_fma_f32 v57, v57, v73, v69
	v_mul_f32_e64 v80, v92, v64
	v_mul_f32_e64 v81, v93, v65
	v_mul_f32_e64 v53, v57, v52
	v_mul_f32_e64 v52, v56, v52
	v_mov_b32_e32 v61, v164
	v_mul_f32_e64 v56, v96, v52
	v_mul_f32_e64 v57, v97, v53
	s_nop 0
	v_add_f32_e32 v56, 0, v56
	v_add_f32_e32 v56, v57, v56
	v_add_f32_e32 v56, v81, v56
	v_add_f32_e32 v56, v80, v56
	s_nop 1
	v_add_f32_dpp v56, v56, v56 quad_perm:[1,0,3,2] row_mask:0xf bank_mask:0xf bound_ctrl:1
	s_nop 1
	v_add_f32_dpp v56, v56, v56 quad_perm:[2,3,0,1] row_mask:0xf bank_mask:0xf bound_ctrl:1
	s_nop 1
	v_add_f32_dpp v56, v56, v56 row_ror:4 row_mask:0xf bank_mask:0xf bound_ctrl:1
	s_nop 1
	v_add_f32_dpp v56, v56, v56 row_ror:8 row_mask:0xf bank_mask:0xf bound_ctrl:1
	v_mul_f32_e32 v56, 0x3c800000, v56
	v_fma_f32 v68, v96, v52, -v56
	v_fma_f32 v69, v97, v53, -v56
	v_fma_f32 v72, v92, v64, -v56
	v_fma_f32 v73, v93, v65, -v56
	v_mul_f32_e64 v52, v68, v68
	v_mul_f32_e64 v53, v69, v69
	v_mul_f32_e64 v56, v72, v72
	v_mul_f32_e64 v57, v73, v73
	v_mov_b32_e32 v60, v52
	v_mov_b32_e32 v164, v53
	v_add_f32_e64 v52, v60, v164
	v_add_f32_e64 v53, v61, v165
	v_mov_b32_e32 v60, v57
	v_mov_b32_e32 v61, v163
	v_add_f32_e64 v52, v60, v52
	v_add_f32_e64 v53, v61, v53
	v_mov_b32_e32 v57, v162
	v_add_f32_e64 v52, v56, v52
	v_add_f32_e64 v53, v57, v53
	v_mov_b64_e32 v[60:61], s[0:1]
	s_movk_i32 s0, 0x1000
	v_mov_b32_dpp v57, v53 quad_perm:[1,0,3,2] row_mask:0xf bank_mask:0xf bound_ctrl:1
	v_mov_b32_dpp v56, v52 quad_perm:[1,0,3,2] row_mask:0xf bank_mask:0xf bound_ctrl:1
	v_add_f32_e64 v52, v52, v56
	v_add_f32_e64 v53, v53, v57
	v_mov_b32_e32 v96, v86
	v_mov_b32_e32 v97, v82
	v_mov_b32_dpp v57, v53 quad_perm:[2,3,0,1] row_mask:0xf bank_mask:0xf bound_ctrl:1
	v_mov_b32_dpp v56, v52 quad_perm:[2,3,0,1] row_mask:0xf bank_mask:0xf bound_ctrl:1
	v_add_f32_e64 v52, v52, v56
	v_add_f32_e64 v53, v53, v57
	s_nop 1
	v_mov_b32_dpp v57, v53 row_ror:4 row_mask:0xf bank_mask:0xf bound_ctrl:1
	v_mov_b32_dpp v56, v52 row_ror:4 row_mask:0xf bank_mask:0xf bound_ctrl:1
	v_add_f32_e64 v52, v52, v56
	v_add_f32_e64 v53, v53, v57
	s_nop 1
	v_mov_b32_dpp v57, v53 row_ror:8 row_mask:0xf bank_mask:0xf bound_ctrl:1
	v_mov_b32_dpp v56, v52 row_ror:8 row_mask:0xf bank_mask:0xf bound_ctrl:1
	v_add_f32_e64 v52, v52, v56
	v_add_f32_e64 v53, v53, v57
	v_lshl_add_u64 v[56:57], s[30:31], 0, v[126:127]
	v_fma_f32 v64, v52, s4, v60
	v_fma_f32 v65, v53, s4, v60
	s_nop 0
	v_mul_f32_e32 v52, 0x4b800000, v65
	v_cmp_gt_f32_e32 vcc, s49, v65
	v_mul_f32_e32 v85, 0x4b800000, v64
	s_nop 0
	v_cndmask_b32_e32 v52, v65, v52, vcc
	v_rsq_f32_e32 v53, v52
	ds_read_b32 v52, v113 offset:47616
	v_mul_f32_e32 v65, 0x45800000, v53
	v_cndmask_b32_e32 v53, v53, v65, vcc
	v_mul_f32_e32 v65, v160, v53
	s_waitcnt vmcnt(3)
	v_mul_f32_e32 v65, v89, v65
	v_med3_f32 v65, v65, s57, v194
	v_cvt_f16_f32_e32 v65, v65
	v_add_co_u32_e32 v80, vcc, s0, v56
	v_mul_f32_e32 v77, v159, v53
	s_nop 0
	v_addc_co_u32_e32 v81, vcc, 0, v57, vcc
	global_store_short v[80:81], v65, off offset:1536
	v_mul_f32_e32 v65, v161, v53
	s_waitcnt vmcnt(3)
	v_mul_f32_e32 v65, v88, v65
	v_cmp_gt_f32_e32 vcc, s49, v64
	v_med3_f32 v65, v65, s57, v194
	s_waitcnt vmcnt(2)
	v_mul_f32_e32 v77, v84, v77
	v_mul_f32_e32 v53, v158, v53
	v_cndmask_b32_e32 v64, v64, v85, vcc
	v_cvt_f16_f32_e32 v65, v65
	v_med3_f32 v77, v77, s57, v194
	s_waitcnt vmcnt(1)
	v_mul_f32_e32 v53, v76, v53
	v_rsq_f32_e32 v64, v64
	v_cvt_f16_f32_e32 v77, v77
	v_med3_f32 v53, v53, s57, v194
	v_cvt_f16_f32_e32 v53, v53
	global_store_short v[80:81], v65, off offset:1568
	global_store_short v[80:81], v77, off offset:1600
	global_store_short v[80:81], v53, off offset:1632
	v_mul_f32_e32 v53, 0x45800000, v64
	v_cndmask_b32_e32 v53, v64, v53, vcc
	v_mul_f32_e32 v64, v68, v53
	v_mul_f32_e32 v64, v89, v64
	v_med3_f32 v64, v64, s57, v194
	v_cvt_f16_f32_e32 v68, v64
	v_add_co_u32_e32 v64, vcc, s48, v56
	s_movk_i32 s0, 0x6000
	s_nop 0
	v_addc_co_u32_e32 v65, vcc, 0, v57, vcc
	global_store_short v[64:65], v68, off offset:3840
	v_mul_f32_e32 v68, v69, v53
	v_mul_f32_e32 v68, v88, v68
	v_med3_f32 v68, v68, s57, v194
	v_cvt_f16_f32_e32 v77, v68
	v_mul_f32_e32 v68, v73, v53
	v_mul_f32_e32 v68, v84, v68
	v_med3_f32 v68, v68, s57, v194
	v_cvt_f16_f32_e32 v85, v68
	v_fma_f32 v68, v74, v98, v94
	v_max_f32_e32 v69, v90, v90
	v_mul_f32_e32 v53, v72, v53
	v_max_f32_e64 v72, |v68|, v69
	v_div_scale_f32 v68, s[16:17], v72, v72, 1.0
	v_rcp_f32_e32 v69, v68
	v_mul_f32_e32 v53, v76, v53
	v_med3_f32 v53, v53, s57, v194
	v_cvt_f16_f32_e32 v53, v53
	v_fma_f32 v73, -v68, v69, 1.0
	v_fmac_f32_e32 v69, v73, v69
	v_div_scale_f32 v73, vcc, 1.0, v72, 1.0
	v_mul_f32_e32 v80, v73, v69
	v_fma_f32 v81, -v68, v80, v73
	v_fmac_f32_e32 v80, v81, v69
	v_fma_f32 v68, -v68, v80, v73
	v_cvt_f32_f16_e32 v73, v152
	v_div_fmas_f32 v80, v68, v69, v80
	v_cvt_f32_f16_e32 v68, v151
	v_cvt_f32_f16_e32 v81, v150
	v_mul_f32_e32 v69, 0xbfb8aa3b, v73
	v_exp_f32_e32 v69, v69
	v_mul_f32_e32 v68, 0xbfb8aa3b, v68
	v_exp_f32_e32 v68, v68
	v_mul_f32_e32 v73, 0xbfb8aa3b, v81
	v_cvt_f32_f16_e32 v81, v149
	v_div_fixup_f32 v72, v80, v72, 1.0
	v_add_f32_e64 v68, v68, 1.0
	v_add_f32_e64 v69, v69, 1.0
	v_exp_f32_e32 v80, v73
	v_div_scale_f32 v90, s[16:17], v69, v69, 1.0
	v_rcp_f32_e32 v92, v90
	v_mul_f32_e32 v73, 0xbfb8aa3b, v81
	v_exp_f32_e32 v81, v73
	v_mov_b32_e32 v150, v54
	v_fma_f32 v73, -v90, v92, 1.0
	v_fmac_f32_e32 v92, v73, v92
	v_div_scale_f32 v73, vcc, 1.0, v69, 1.0
	v_mul_f32_e32 v93, v73, v92
	v_fma_f32 v94, -v90, v93, v73
	v_fmac_f32_e32 v93, v94, v92
	v_fma_f32 v73, -v90, v93, v73
	v_div_scale_f32 v90, s[16:17], v68, v68, 1.0
	v_rcp_f32_e32 v94, v90
	v_div_fmas_f32 v73, v73, v92, v93
	v_div_fixup_f32 v69, v73, v69, 1.0
	v_add_f32_e64 v80, v80, 1.0
	v_add_f32_e64 v81, v81, 1.0
	v_fma_f32 v73, -v90, v94, 1.0
	v_fmac_f32_e32 v94, v73, v94
	v_div_scale_f32 v73, vcc, 1.0, v68, 1.0
	v_mul_f32_e32 v92, v73, v94
	v_fma_f32 v93, -v90, v92, v73
	v_fmac_f32_e32 v92, v93, v94
	v_fma_f32 v73, -v90, v92, v73
	v_div_fmas_f32 v73, v73, v94, v92
	v_mov_b32_e32 v93, v66
	v_div_scale_f32 v66, s[16:17], v81, v81, 1.0
	v_div_fixup_f32 v68, v73, v68, 1.0
	v_rcp_f32_e32 v73, v66
	v_mov_b32_e32 v92, v78
	v_fma_f32 v92, v92, v74, v96
	v_fma_f32 v93, v93, v74, v97
	v_mov_b32_e32 v151, v58
	v_fma_f32 v78, -v66, v73, 1.0
	v_mul_f32_e64 v92, v92, v72
	v_mul_f32_e64 v93, v93, v72
	v_fmac_f32_e32 v73, v78, v73
	v_div_scale_f32 v78, vcc, 1.0, v81, 1.0
	v_mul_f32_e32 v82, v78, v73
	v_fma_f32 v86, -v66, v82, v78
	v_fmac_f32_e32 v82, v86, v73
	v_fma_f32 v66, -v66, v82, v78
	v_div_scale_f32 v78, s[16:17], v80, v80, 1.0
	v_rcp_f32_e32 v86, v78
	v_div_fmas_f32 v66, v66, v73, v82
	v_div_fixup_f32 v81, v66, v81, 1.0
	v_mov_b32_e32 v152, v62
	v_fma_f32 v66, -v78, v86, 1.0
	v_fmac_f32_e32 v86, v66, v86
	v_div_scale_f32 v66, vcc, 1.0, v80, 1.0
	v_mul_f32_e32 v73, v66, v86
	v_fma_f32 v82, -v78, v73, v66
	v_fmac_f32_e32 v73, v82, v86
	v_fma_f32 v66, -v78, v73, v66
	v_div_fmas_f32 v66, v66, v86, v73
	v_fma_f32 v150, v150, v74, v152
	v_fma_f32 v151, v151, v74, v153
	v_div_fixup_f32 v80, v66, v80, 1.0
	v_mul_f32_e64 v73, v151, v72
	v_mul_f32_e64 v72, v150, v72
	v_mul_f32_e64 v96, v68, v92
	v_mul_f32_e64 v97, v69, v93
	v_mul_f32_e64 v150, v80, v72
	v_mul_f32_e64 v151, v81, v73
	v_max_f32_e32 v58, v91, v91
	v_add_f32_e32 v54, 0, v150
	v_add_f32_e32 v54, v151, v54
	v_add_f32_e32 v54, v97, v54
	v_add_f32_e32 v54, v96, v54
	v_max_f32_e64 v58, |v95|, v58
	v_div_scale_f32 v62, s[16:17], v58, v58, 1.0
	v_add_f32_dpp v54, v54, v54 quad_perm:[1,0,3,2] row_mask:0xf bank_mask:0xf bound_ctrl:1
	v_rcp_f32_e32 v66, v62
	v_mov_b32_e32 v82, v87
	v_add_f32_dpp v54, v54, v54 quad_perm:[2,3,0,1] row_mask:0xf bank_mask:0xf bound_ctrl:1
	global_store_short v[64:65], v77, off offset:3872
	global_store_short v[64:65], v85, off offset:3904
	global_store_short v[64:65], v53, off offset:3936
	v_add_f32_dpp v54, v54, v54 row_ror:4 row_mask:0xf bank_mask:0xf bound_ctrl:1
	s_nop 1
	v_add_f32_dpp v54, v54, v54 row_ror:8 row_mask:0xf bank_mask:0xf bound_ctrl:1
	v_mul_f32_e32 v54, 0x3c800000, v54
	v_fma_f32 v72, v80, v72, -v54
	v_fma_f32 v73, v81, v73, -v54
	v_fma_f32 v68, v68, v92, -v54
	v_fma_f32 v69, v69, v93, -v54
	v_fma_f32 v54, -v62, v66, 1.0
	v_fmac_f32_e32 v66, v54, v66
	v_div_scale_f32 v54, vcc, 1.0, v58, 1.0
	v_mul_f32_e32 v70, v54, v66
	v_fma_f32 v74, -v62, v70, v54
	v_fmac_f32_e32 v70, v74, v66
	v_fma_f32 v54, -v62, v70, v54
	v_cvt_f32_f16_e32 v62, v148
	v_div_fmas_f32 v54, v54, v66, v70
	v_cvt_f32_f16_e32 v66, v147
	v_cvt_f32_f16_e32 v70, v146
	v_mul_f32_e32 v62, 0xbfb8aa3b, v62
	v_exp_f32_e32 v93, v62
	v_mul_f32_e32 v62, 0xbfb8aa3b, v66
	v_exp_f32_e32 v92, v62
	v_cvt_f32_f16_e32 v62, v112
	v_div_fixup_f32 v54, v54, v58, 1.0
	v_mul_f32_e32 v58, 0xbfb8aa3b, v70
	v_add_f32_e64 v92, v92, 1.0
	v_add_f32_e64 v93, v93, 1.0
	v_exp_f32_e32 v94, v58
	v_div_scale_f32 v66, s[16:17], v93, v93, 1.0
	v_rcp_f32_e32 v70, v66
	v_mul_f32_e32 v58, 0xbfb8aa3b, v62
	v_exp_f32_e32 v95, v58
	v_mul_f32_e64 v80, v72, v72
	v_mul_f32_e64 v81, v73, v73
	v_fma_f32 v58, -v66, v70, 1.0
	v_fmac_f32_e32 v70, v58, v70
	v_div_scale_f32 v58, vcc, 1.0, v93, 1.0
	v_mul_f32_e32 v62, v58, v70
	v_fma_f32 v74, -v66, v62, v58
	v_fmac_f32_e32 v62, v74, v70
	v_fma_f32 v58, -v66, v62, v58
	v_div_scale_f32 v66, s[16:17], v92, v92, 1.0
	v_rcp_f32_e32 v74, v66
	v_div_fmas_f32 v58, v58, v70, v62
	v_div_fixup_f32 v93, v58, v93, 1.0
	v_mul_f32_e64 v90, v68, v68
	v_mul_f32_e64 v91, v69, v69
	v_fma_f32 v58, -v66, v74, 1.0
	v_fmac_f32_e32 v74, v58, v74
	v_div_scale_f32 v58, vcc, 1.0, v92, 1.0
	v_mul_f32_e32 v62, v58, v74
	v_fma_f32 v70, -v66, v62, v58
	v_fmac_f32_e32 v62, v70, v74
	v_fma_f32 v58, -v66, v62, v58
	v_div_fmas_f32 v58, v58, v74, v62
	v_mov_b32_e32 v62, v75
	v_add_f32_e64 v74, v94, 1.0
	v_add_f32_e64 v75, v95, 1.0
	v_div_fixup_f32 v92, v58, v92, 1.0
	v_div_scale_f32 v58, s[16:17], v75, v75, 1.0
	v_rcp_f32_e32 v70, v58
	v_mov_b32_e32 v66, v79
	v_fma_f32 v66, v66, v62, v82
	v_fma_f32 v67, v67, v62, v83
	v_fma_f32 v82, -v58, v70, 1.0
	v_fmac_f32_e32 v70, v82, v70
	v_div_scale_f32 v82, vcc, 1.0, v75, 1.0
	v_mul_f32_e32 v83, v82, v70
	v_fma_f32 v86, -v58, v83, v82
	v_fmac_f32_e32 v83, v86, v70
	v_fma_f32 v58, -v58, v83, v82
	v_div_scale_f32 v82, s[16:17], v74, v74, 1.0
	v_rcp_f32_e32 v86, v82
	v_div_fmas_f32 v58, v58, v70, v83
	v_div_fixup_f32 v75, v58, v75, 1.0
	v_mul_f32_e64 v66, v66, v54
	v_mul_f32_e64 v67, v67, v54
	v_fma_f32 v58, -v82, v86, 1.0
	v_fmac_f32_e32 v86, v58, v86
	v_div_scale_f32 v58, vcc, 1.0, v74, 1.0
	v_mul_f32_e32 v70, v58, v86
	v_fma_f32 v83, -v82, v70, v58
	v_fmac_f32_e32 v70, v83, v86
	v_fma_f32 v58, -v82, v70, v58
	v_div_fmas_f32 v58, v58, v86, v70
	v_div_fixup_f32 v74, v58, v74, 1.0
	v_mov_b32_e32 v58, v55
	v_mov_b32_e32 v70, v63
	v_fma_f32 v58, v58, v62, v70
	v_fma_f32 v59, v59, v62, v71
	v_mul_f32_e64 v78, v92, v66
	v_mul_f32_e64 v79, v93, v67
	v_mul_f32_e64 v55, v59, v54
	v_mul_f32_e64 v54, v58, v54
	s_nop 0
	v_mul_f32_e64 v58, v74, v54
	v_mul_f32_e64 v59, v75, v55
	s_nop 0
	v_add_f32_e32 v58, 0, v58
	v_add_f32_e32 v58, v59, v58
	v_add_f32_e32 v58, v79, v58
	v_add_f32_e32 v58, v78, v58
	s_nop 1
	v_add_f32_dpp v58, v58, v58 quad_perm:[1,0,3,2] row_mask:0xf bank_mask:0xf bound_ctrl:1
	s_nop 1
	v_add_f32_dpp v58, v58, v58 quad_perm:[2,3,0,1] row_mask:0xf bank_mask:0xf bound_ctrl:1
	s_nop 1
	v_add_f32_dpp v58, v58, v58 row_ror:4 row_mask:0xf bank_mask:0xf bound_ctrl:1
	s_nop 1
	v_add_f32_dpp v58, v58, v58 row_ror:8 row_mask:0xf bank_mask:0xf bound_ctrl:1
	v_mul_f32_e32 v58, 0x3c800000, v58
	v_fma_f32 v54, v74, v54, -v58
	v_fma_f32 v55, v75, v55, -v58
	v_fma_f32 v74, v92, v66, -v58
	v_fma_f32 v75, v93, v67, -v58
	v_mul_f32_e64 v62, v54, v54
	v_mul_f32_e64 v63, v55, v55
	v_mul_f32_e64 v58, v74, v74
	v_mul_f32_e64 v59, v75, v75
	v_mov_b32_e32 v66, v62
	v_mov_b32_e32 v67, v80
	v_mov_b32_e32 v80, v63
	v_add_f32_e64 v62, v66, v80
	v_add_f32_e64 v63, v67, v81
	v_mov_b32_e32 v66, v59
	v_mov_b32_e32 v67, v91
	v_add_f32_e64 v62, v66, v62
	v_add_f32_e64 v63, v67, v63
	v_mov_b32_e32 v59, v90
	v_add_f32_e64 v58, v58, v62
	v_add_f32_e64 v59, v59, v63
	s_nop 1
	v_mov_b32_dpp v63, v59 quad_perm:[1,0,3,2] row_mask:0xf bank_mask:0xf bound_ctrl:1
	v_mov_b32_dpp v62, v58 quad_perm:[1,0,3,2] row_mask:0xf bank_mask:0xf bound_ctrl:1
	v_add_f32_e64 v58, v58, v62
	v_add_f32_e64 v59, v59, v63
	s_nop 1
	v_mov_b32_dpp v63, v59 quad_perm:[2,3,0,1] row_mask:0xf bank_mask:0xf bound_ctrl:1
	v_mov_b32_dpp v62, v58 quad_perm:[2,3,0,1] row_mask:0xf bank_mask:0xf bound_ctrl:1
	v_add_f32_e64 v58, v58, v62
	v_add_f32_e64 v59, v59, v63
	s_nop 1
	v_mov_b32_dpp v63, v59 row_ror:4 row_mask:0xf bank_mask:0xf bound_ctrl:1
	v_mov_b32_dpp v62, v58 row_ror:4 row_mask:0xf bank_mask:0xf bound_ctrl:1
	v_add_f32_e64 v58, v58, v62
	v_add_f32_e64 v59, v59, v63
	s_nop 1
	v_mov_b32_dpp v63, v59 row_ror:8 row_mask:0xf bank_mask:0xf bound_ctrl:1
	v_mov_b32_dpp v62, v58 row_ror:8 row_mask:0xf bank_mask:0xf bound_ctrl:1
	v_add_f32_e64 v58, v58, v62
	v_add_f32_e64 v59, v59, v63
	s_nop 0
	v_fma_f32 v58, v58, s4, v60
	v_fma_f32 v59, v59, s4, v60
	s_nop 0
	v_mul_f32_e32 v60, 0x4b800000, v59
	v_cmp_gt_f32_e32 vcc, s49, v59
	v_mul_f32_e32 v63, 0x4b800000, v58
	s_nop 0
	v_cndmask_b32_e32 v59, v59, v60, vcc
	v_rsq_f32_e32 v59, v59
	s_nop 0
	v_mul_f32_e32 v53, 0x45800000, v59
	v_cndmask_b32_e32 v53, v59, v53, vcc
	v_mul_f32_e32 v59, v72, v53
	v_mul_f32_e32 v59, v89, v59
	v_med3_f32 v59, v59, s57, v194
	v_cvt_f16_f32_e32 v59, v59
	v_add_co_u32_e32 v60, vcc, s56, v56
	v_mul_f32_e32 v62, v69, v53
	s_nop 0
	v_addc_co_u32_e32 v61, vcc, 0, v57, vcc
	global_store_short v[60:61], v59, off offset:2048
	v_mul_f32_e32 v59, v73, v53
	v_mul_f32_e32 v59, v88, v59
	v_cmp_gt_f32_e32 vcc, s49, v58
	v_med3_f32 v59, v59, s57, v194
	v_mul_f32_e32 v62, v84, v62
	v_mul_f32_e32 v53, v68, v53
	v_cndmask_b32_e32 v58, v58, v63, vcc
	v_cvt_f16_f32_e32 v59, v59
	v_med3_f32 v62, v62, s57, v194
	v_mul_f32_e32 v53, v76, v53
	v_rsq_f32_e32 v58, v58
	v_cvt_f16_f32_e32 v62, v62
	v_med3_f32 v53, v53, s57, v194
	v_cvt_f16_f32_e32 v53, v53
	global_store_short v[60:61], v59, off offset:2080
	global_store_short v[60:61], v62, off offset:2112
	global_store_short v[60:61], v53, off offset:2144
	v_mul_f32_e32 v53, 0x45800000, v58
	v_cndmask_b32_e32 v53, v58, v53, vcc
	v_mul_f32_e32 v54, v54, v53
	v_mul_f32_e32 v54, v89, v54
	v_med3_f32 v54, v54, s57, v194
	v_cvt_f16_f32_e32 v54, v54
	v_add_co_u32_e32 v82, vcc, s0, v56
	ds_read_b128 v[58:61], v101 offset:18432
	s_nop 0
	v_addc_co_u32_e32 v83, vcc, 0, v57, vcc
	global_store_short v[82:83], v54, off offset:256
	v_mul_f32_e32 v54, v55, v53
	v_mul_f32_e32 v54, v88, v54
	v_med3_f32 v77, v54, s57, v194
	ds_read_b128 v[54:57], v100 offset:27648
	ds_read_b128 v[62:65], v101 offset:20736
	ds_read_b128 v[66:69], v100 offset:27712
	ds_read_b128 v[70:73], v101 offset:18496
	s_waitcnt lgkmcnt(5)
	v_mul_f32_e64 v50, v50, v52
	v_mul_f32_e64 v51, v51, v52
	v_mul_f32_e64 v48, v48, v52
	v_mul_f32_e64 v49, v49, v52
	v_mul_f32_e64 v46, v46, v52
	v_mul_f32_e64 v47, v47, v52
	v_mul_f32_e64 v44, v44, v52
	v_mul_f32_e64 v45, v45, v52
	s_waitcnt lgkmcnt(3)
	v_mfma_f32_16x16x32_f16 v[48:51], v[54:57], v[58:61], v[48:51]
	ds_read_b128 v[58:61], v101 offset:23040
	ds_read_b128 v[78:81], v101 offset:20800
	v_mul_f32_e64 v42, v42, v52
	v_mul_f32_e64 v43, v43, v52
	v_mul_f32_e64 v40, v40, v52
	v_mul_f32_e64 v41, v41, v52
	s_waitcnt lgkmcnt(4)
	v_mfma_f32_16x16x32_f16 v[44:47], v[54:57], v[62:65], v[44:47]
	ds_read_b128 v[62:65], v101 offset:25344
	ds_read_b128 v[86:89], v101 offset:23104
	v_mul_f32_e64 v38, v38, v52
	v_mul_f32_e64 v39, v39, v52
	v_mul_f32_e64 v36, v36, v52
	v_mul_f32_e64 v37, v37, v52
	s_waitcnt lgkmcnt(3)
	v_mfma_f32_16x16x32_f16 v[40:43], v[54:57], v[58:61], v[40:43]
	ds_read_b128 v[58:61], v101 offset:25408
	s_waitcnt lgkmcnt(2)
	v_mfma_f32_16x16x32_f16 v[36:39], v[54:57], v[62:65], v[36:39]
	v_mul_f32_e32 v55, v75, v53
	v_mul_f32_e32 v55, v84, v55
	v_mul_f32_e32 v53, v74, v53
	v_cvt_f16_f32_e32 v54, v77
	v_med3_f32 v55, v55, s57, v194
	v_mul_f32_e32 v53, v76, v53
	v_mfma_f32_16x16x32_f16 v[48:51], v[66:69], v[70:73], v[48:51]
	v_cvt_f16_f32_e32 v55, v55
	v_med3_f32 v53, v53, s57, v194
	v_cvt_f16_f32_e32 v53, v53
	v_mfma_f32_16x16x32_f16 v[44:47], v[66:69], v[78:81], v[44:47]
	global_store_short v[82:83], v54, off offset:288
	global_store_short v[82:83], v55, off offset:320
	global_store_short v[82:83], v53, off offset:352
	v_mov_b32_e32 v55, 0
	s_waitcnt lgkmcnt(1)
	v_mfma_f32_16x16x32_f16 v[40:43], v[66:69], v[86:89], v[40:43]
	s_waitcnt lgkmcnt(0)
	v_mfma_f32_16x16x32_f16 v[36:39], v[66:69], v[58:61], v[36:39]
	s_and_saveexec_b64 s[16:17], s[8:9]
	s_cbranch_execz .LBB0_509
	ds_read2st64_b32 v[54:55], v143 offset0:180 offset1:185
	s_waitcnt lgkmcnt(0)
	v_fmac_f32_e32 v55, v52, v54

.Lscan_pfA_skip:
	s_mov_b32 s0, 0x358637bd
	ds_read_b128 v[108:111], v116 offset:46080
	ds_read_b128 v[240:243], v117
	ds_read_b128 v[244:247], v117 offset:2304
	ds_read_b128 v[252:255], v117 offset:4608
	s_waitcnt lgkmcnt(2)
	v_mfma_f32_16x16x32_f16 v[236:239], v[108:111], v[240:243], 0
	ds_read_b128 v[240:243], v117 offset:6912
	ds_read_b128 v[174:177], v116 offset:46144
	s_waitcnt lgkmcnt(3)
	v_mfma_f32_16x16x32_f16 v[104:107], v[108:111], v[244:247], 0
	ds_read_b128 v[244:247], v117 offset:64
	s_waitcnt lgkmcnt(3)
	v_mfma_f32_16x16x32_f16 v[100:103], v[108:111], v[252:255], 0
	ds_read_b128 v[252:255], v117 offset:2368
	s_waitcnt lgkmcnt(3)
	v_mfma_f32_16x16x32_f16 v[96:99], v[108:111], v[240:243], 0
	ds_read_b128 v[240:243], v117 offset:4672
	s_waitcnt lgkmcnt(2)
	v_mfma_f32_16x16x32_f16 v[236:239], v[174:177], v[244:247], v[236:239]
	ds_read_b128 v[244:247], v117 offset:6976
	s_waitcnt lgkmcnt(2)
	v_mfma_f32_16x16x32_f16 v[104:107], v[174:177], v[252:255], v[104:107]
	s_waitcnt lgkmcnt(1)
	v_mfma_f32_16x16x32_f16 v[100:103], v[174:177], v[240:243], v[100:103]
	s_waitcnt lgkmcnt(0)
	v_mfma_f32_16x16x32_f16 v[96:99], v[174:177], v[244:247], v[96:99]
	ds_read_b64 v[108:109], v214 offset:9216
	s_waitcnt lgkmcnt(0)
	v_cvt_f32_f16_e32 v110, v108
	v_cvt_f32_f16_sdwa v108, v108 dst_sel:DWORD dst_unused:UNUSED_PAD src0_sel:WORD_1
	v_sub_f32_e32 v110, v110, v236
	v_sub_f32_e32 v108, v108, v237
	v_med3_f32 v108, v108, s57, v194
	v_cvt_f16_f32_e32 v108, v108
	v_med3_f32 v110, v110, s57, v194
	v_cvt_f16_f32_e32 v110, v110
	ds_write_b16 v215, v108 offset:55440
	v_cvt_f32_f16_e32 v108, v109
	ds_write_b16 v215, v110 offset:55296
	v_sub_f32_e32 v108, v108, v238
	v_med3_f32 v108, v108, s57, v194
	v_cvt_f16_f32_e32 v108, v108
	ds_write_b16 v215, v108 offset:55584
	v_cvt_f32_f16_sdwa v108, v109 dst_sel:DWORD dst_unused:UNUSED_PAD src0_sel:WORD_1
	v_sub_f32_e32 v108, v108, v239
	v_med3_f32 v108, v108, s57, v194
	v_cvt_f16_f32_e32 v108, v108
	ds_write_b16 v215, v108 offset:55728
	ds_read_b64 v[108:109], v214 offset:11520
	s_waitcnt lgkmcnt(0)
	v_cvt_f32_f16_e32 v110, v108
	v_sub_f32_e32 v104, v110, v104
	v_med3_f32 v104, v104, s57, v194
	v_cvt_f16_f32_e32 v104, v104
	ds_write_b16 v215, v104 offset:55328
	v_cvt_f32_f16_sdwa v104, v108 dst_sel:DWORD dst_unused:UNUSED_PAD src0_sel:WORD_1
	v_sub_f32_e32 v104, v104, v105
	v_med3_f32 v104, v104, s57, v194
	v_cvt_f16_f32_e32 v104, v104
	ds_write_b16 v216, v104 offset:55440
	v_cvt_f32_f16_e32 v104, v109
	v_sub_f32_e32 v104, v104, v106
	v_med3_f32 v104, v104, s57, v194
	v_cvt_f16_f32_e32 v104, v104
	ds_write_b16 v216, v104 offset:55584
	v_cvt_f32_f16_sdwa v104, v109 dst_sel:DWORD dst_unused:UNUSED_PAD src0_sel:WORD_1
	v_sub_f32_e32 v104, v104, v107
	v_med3_f32 v104, v104, s57, v194
	v_cvt_f16_f32_e32 v104, v104
	ds_write_b16 v216, v104 offset:55728
	ds_read_b64 v[104:105], v214 offset:13824
	s_waitcnt lgkmcnt(0)
	v_cvt_f32_f16_e32 v106, v104
	v_sub_f32_e32 v100, v106, v100
	v_med3_f32 v100, v100, s57, v194
	v_cvt_f16_f32_e32 v100, v100
	ds_write_b16 v215, v100 offset:55360
	v_cvt_f32_f16_sdwa v100, v104 dst_sel:DWORD dst_unused:UNUSED_PAD src0_sel:WORD_1
	v_sub_f32_e32 v100, v100, v101
	v_med3_f32 v100, v100, s57, v194
	v_cvt_f16_f32_e32 v100, v100
	ds_write_b16 v217, v100 offset:55440
	v_cvt_f32_f16_e32 v100, v105
	v_sub_f32_e32 v100, v100, v102
	v_med3_f32 v100, v100, s57, v194
	v_cvt_f16_f32_e32 v100, v100
	ds_write_b16 v217, v100 offset:55584
	v_cvt_f32_f16_sdwa v100, v105 dst_sel:DWORD dst_unused:UNUSED_PAD src0_sel:WORD_1
	v_sub_f32_e32 v100, v100, v103
	v_med3_f32 v100, v100, s57, v194
	v_cvt_f16_f32_e32 v100, v100
	ds_write_b16 v217, v100 offset:55728
	ds_read_b64 v[100:101], v214 offset:16128
	s_waitcnt lgkmcnt(0)
	v_cvt_f32_f16_e32 v102, v100
	v_sub_f32_e32 v96, v102, v96
	v_med3_f32 v96, v96, s57, v194
	v_cvt_f16_f32_e32 v96, v96
	ds_write_b16 v215, v96 offset:55392
	v_cvt_f32_f16_sdwa v96, v100 dst_sel:DWORD dst_unused:UNUSED_PAD src0_sel:WORD_1
	v_sub_f32_e32 v96, v96, v97
	v_med3_f32 v96, v96, s57, v194
	v_cvt_f16_f32_e32 v96, v96
	ds_write_b16 v218, v96 offset:55440
	v_cvt_f32_f16_e32 v96, v101
	v_sub_f32_e32 v96, v96, v98
	v_med3_f32 v96, v96, s57, v194
	v_cvt_f16_f32_e32 v96, v96
	ds_write_b16 v218, v96 offset:55584
	v_cvt_f32_f16_sdwa v96, v101 dst_sel:DWORD dst_unused:UNUSED_PAD src0_sel:WORD_1
	v_sub_f32_e32 v96, v96, v99
	v_med3_f32 v96, v96, s57, v194
	v_cvt_f16_f32_e32 v96, v96
	ds_write_b16 v218, v96 offset:55728
	s_waitcnt lgkmcnt(0)
	s_barrier
	ds_write_b128 v115, v[0:3]
	ds_write_b128 v209, v[4:7]
	ds_write_b128 v219, v[8:11]
	ds_write_b128 v210, v[12:15]
	s_waitcnt vmcnt(15)
	v_cvt_f32_f16_e32 v235, v234
	global_load_dword v234, v[118:119], off
	ds_read_b128 v[174:177], v116 offset:27648
	ds_read_b128 v[240:243], v117 offset:46080
	ds_read_b128 v[244:247], v117 offset:48384
	ds_read_b128 v[252:255], v117 offset:50688
	s_waitcnt lgkmcnt(2)
	v_mfma_f32_16x16x32_f16 v[108:111], v[174:177], v[240:243], 0
	ds_read_b128 v[240:243], v117 offset:52992
	ds_read_b128 v[236:239], v116 offset:27712
	s_waitcnt lgkmcnt(3)
	v_mfma_f32_16x16x32_f16 v[104:107], v[174:177], v[244:247], 0
	ds_read_b128 v[244:247], v117 offset:46144
	s_waitcnt lgkmcnt(3)
	v_mfma_f32_16x16x32_f16 v[100:103], v[174:177], v[252:255], 0
	ds_read_b128 v[252:255], v117 offset:48448
	s_waitcnt lgkmcnt(3)
	v_mfma_f32_16x16x32_f16 v[96:99], v[174:177], v[240:243], 0
	ds_read_b128 v[240:243], v117 offset:50752
	s_waitcnt lgkmcnt(2)
	v_mfma_f32_16x16x32_f16 v[108:111], v[236:239], v[244:247], v[108:111]
	ds_read_b128 v[244:247], v117 offset:53056
	ds_read_b128 v[174:177], v116 offset:18432
	s_waitcnt lgkmcnt(3)
	v_mfma_f32_16x16x32_f16 v[104:107], v[236:239], v[252:255], v[104:107]
	ds_read_b128 v[252:255], v117 offset:55296
	s_waitcnt lgkmcnt(3)
	v_mfma_f32_16x16x32_f16 v[100:103], v[236:239], v[240:243], v[100:103]
	ds_read_b128 v[240:243], v117 offset:57600
	s_waitcnt lgkmcnt(3)
	v_mfma_f32_16x16x32_f16 v[96:99], v[236:239], v[244:247], v[96:99]
	ds_read_b128 v[244:247], v117 offset:59904
	s_waitcnt lgkmcnt(2)
	v_mfma_f32_16x16x32_f16 v[108:111], v[174:177], v[252:255], v[108:111]
	ds_read_b128 v[252:255], v117 offset:62208
	ds_read_b128 v[236:239], v116 offset:18496
	s_waitcnt lgkmcnt(3)
	v_mfma_f32_16x16x32_f16 v[104:107], v[174:177], v[240:243], v[104:107]
	ds_read_b128 v[240:243], v117 offset:55360
	s_waitcnt lgkmcnt(3)
	v_mfma_f32_16x16x32_f16 v[100:103], v[174:177], v[244:247], v[100:103]
	ds_read_b128 v[244:247], v117 offset:57664
	s_waitcnt lgkmcnt(3)
	v_mfma_f32_16x16x32_f16 v[96:99], v[174:177], v[252:255], v[96:99]
	ds_read_b128 v[252:255], v117 offset:59968
	s_waitcnt lgkmcnt(2)
	v_mfma_f32_16x16x32_f16 v[108:111], v[236:239], v[240:243], v[108:111]
	ds_read_b128 v[240:243], v117 offset:62272
	s_waitcnt lgkmcnt(2)
	v_mfma_f32_16x16x32_f16 v[104:107], v[236:239], v[244:247], v[104:107]
	s_waitcnt lgkmcnt(1)
	v_mfma_f32_16x16x32_f16 v[100:103], v[236:239], v[252:255], v[100:103]
	s_waitcnt lgkmcnt(0)
	v_mfma_f32_16x16x32_f16 v[96:99], v[236:239], v[240:243], v[96:99]
	v_mul_f32_e32 v236, 0xbfb8aa3b, v235
	v_exp_f32_e32 v236, v236
	v_mov_b32_e32 v174, v108
	v_mov_b32_e32 v175, v104
	v_mul_f32_e64 v176, v174, v174
	v_mul_f32_e64 v177, v175, v175
	v_add_f32_e32 v236, 1.0, v236
	v_div_scale_f32 v237, s[8:9], v236, v236, v235
	v_rcp_f32_e32 v238, v237
	v_mov_b32_e32 v174, v100
	v_mov_b32_e32 v175, v96
	v_mul_f32_e64 v174, v174, v174
	v_mul_f32_e64 v175, v175, v175
	v_fma_f32 v239, -v237, v238, 1.0
	v_fmac_f32_e32 v238, v239, v238
	v_div_scale_f32 v239, vcc, v235, v236, v235
	v_mul_f32_e32 v240, v239, v238
	v_fma_f32 v241, -v237, v240, v239
	v_fmac_f32_e32 v240, v241, v238
	v_fma_f32 v237, -v237, v240, v239
	v_div_fmas_f32 v237, v237, v238, v240
	v_div_fixup_f32 v235, v237, v236, v235
	s_waitcnt vmcnt(15)
	v_cvt_f32_f16_e32 v236, v233
	global_load_dword v233, v[118:119], off offset:64
	v_mul_f32_e32 v237, 0xbfb8aa3b, v236
	v_exp_f32_e32 v237, v237
	s_nop 0
	v_add_f32_e32 v237, 1.0, v237
	v_div_scale_f32 v238, s[8:9], v237, v237, v236
	v_rcp_f32_e32 v239, v238
	s_nop 0
	v_fma_f32 v240, -v238, v239, 1.0
	v_fmac_f32_e32 v239, v240, v239
	v_div_scale_f32 v240, vcc, v236, v237, v236
	v_mul_f32_e32 v241, v240, v239
	v_fma_f32 v242, -v238, v241, v240
	v_fmac_f32_e32 v241, v242, v239
	v_fma_f32 v238, -v238, v241, v240
	v_div_fmas_f32 v238, v238, v239, v241
	v_div_fixup_f32 v242, v238, v237, v236
	s_waitcnt vmcnt(15)
	v_cvt_f32_f16_e32 v236, v232
	global_load_dword v232, v[118:119], off offset:128
	v_mul_f32_e32 v237, 0xbfb8aa3b, v236
	v_exp_f32_e32 v237, v237
	s_nop 0
	v_add_f32_e32 v237, 1.0, v237
	v_div_scale_f32 v238, s[8:9], v237, v237, v236
	v_rcp_f32_e32 v239, v238
	s_nop 0
	v_fma_f32 v240, -v238, v239, 1.0
	v_fmac_f32_e32 v239, v240, v239
	v_div_scale_f32 v240, vcc, v236, v237, v236
	v_mul_f32_e32 v241, v240, v239
	v_fma_f32 v243, -v238, v241, v240
	v_fmac_f32_e32 v241, v243, v239
	v_fma_f32 v238, -v238, v241, v240
	v_div_fmas_f32 v238, v238, v239, v241
	v_div_fixup_f32 v243, v238, v237, v236
	s_waitcnt vmcnt(15)
	v_cvt_f32_f16_e32 v236, v231
	global_load_dword v231, v[118:119], off offset:192
	v_mul_f32_e32 v237, 0xbfb8aa3b, v236
	v_exp_f32_e32 v237, v237
	s_nop 0
	v_add_f32_e32 v237, 1.0, v237
	v_div_scale_f32 v238, s[8:9], v237, v237, v236
	v_rcp_f32_e32 v239, v238
	s_nop 0
	v_fma_f32 v240, -v238, v239, 1.0
	v_fmac_f32_e32 v239, v240, v239
	v_div_scale_f32 v240, vcc, v236, v237, v236
	v_mul_f32_e32 v241, v240, v239
	v_fma_f32 v244, -v238, v241, v240
	v_fmac_f32_e32 v241, v244, v239
	v_fma_f32 v238, -v238, v241, v240
	v_div_fmas_f32 v238, v238, v239, v241
	v_div_fixup_f32 v244, v238, v237, v236
	v_mov_b32_e32 v236, v109
	v_mov_b32_e32 v237, v105
	v_mul_f32_e64 v236, v236, v236
	v_mul_f32_e64 v237, v237, v237
	v_mov_b32_e32 v238, v101
	v_mov_b32_e32 v239, v97
	v_mul_f32_e64 v238, v238, v238
	v_mul_f32_e64 v239, v239, v239
	v_mov_b32_e32 v240, v236
	v_mov_b32_e32 v241, v176
	v_mov_b32_e32 v176, v237
	v_add_f32_e64 v176, v240, v176
	v_add_f32_e64 v177, v241, v177
	v_mov_b32_e32 v236, v238
	v_mov_b32_e32 v237, v174
	v_add_f32_e64 v176, v176, v236
	v_add_f32_e64 v177, v177, v237
	v_mov_b32_e32 v174, v239
	v_add_f32_e64 v174, v176, v174
	v_add_f32_e64 v175, v177, v175
	s_nop 1
	v_mov_b32_dpp v177, v175 quad_perm:[1,0,3,2] row_mask:0xf bank_mask:0xf bound_ctrl:1
	v_mov_b32_dpp v176, v174 quad_perm:[1,0,3,2] row_mask:0xf bank_mask:0xf bound_ctrl:1
	v_add_f32_e64 v174, v174, v176
	v_add_f32_e64 v175, v175, v177
	s_nop 1
	v_mov_b32_dpp v177, v175 quad_perm:[2,3,0,1] row_mask:0xf bank_mask:0xf bound_ctrl:1
	v_mov_b32_dpp v176, v174 quad_perm:[2,3,0,1] row_mask:0xf bank_mask:0xf bound_ctrl:1
	v_add_f32_e64 v174, v174, v176
	v_add_f32_e64 v175, v175, v177
	s_nop 1
	v_mov_b32_dpp v177, v175 row_ror:4 row_mask:0xf bank_mask:0xf bound_ctrl:1
	v_mov_b32_dpp v176, v174 row_ror:4 row_mask:0xf bank_mask:0xf bound_ctrl:1
	v_add_f32_e64 v174, v174, v176
	v_add_f32_e64 v175, v175, v177
	s_nop 1
	v_mov_b32_dpp v177, v175 row_ror:8 row_mask:0xf bank_mask:0xf bound_ctrl:1
	v_mov_b32_dpp v176, v174 row_ror:8 row_mask:0xf bank_mask:0xf bound_ctrl:1
	v_add_f32_e64 v176, v174, v176
	v_add_f32_e64 v177, v175, v177
	v_mov_b64_e32 v[174:175], s[0:1]
	s_mov_b32 s0, 0x3c800000
	v_fma_f32 v176, v176, s0, v174
	v_fma_f32 v177, v177, s0, v174
	s_nop 0
	v_mul_f32_e32 v236, 0x4b800000, v177
	v_cmp_gt_f32_e64 s[8:9], s49, v177
	v_cmp_gt_f32_e32 vcc, s49, v176
	s_nop 0
	v_cndmask_b32_e64 v177, v177, v236, s[8:9]
	v_rsq_f32_e32 v177, v177
	s_nop 0
	v_mul_f32_e32 v236, 0x45800000, v177
	v_cndmask_b32_e64 v177, v177, v236, s[8:9]
	v_mul_f32_e32 v96, v96, v177
	v_mul_f32_e32 v100, v100, v177
	s_waitcnt vmcnt(1)
	v_mul_f32_e32 v100, v232, v100
	v_mul_f32_e32 v100, v243, v100
	v_med3_f32 v100, v100, s57, v194
	s_waitcnt vmcnt(0)
	v_mul_f32_e32 v96, v231, v96
	v_mul_f32_e32 v96, v244, v96
	v_med3_f32 v96, v96, s57, v194
	v_cvt_f16_f32_e32 v96, v96
	v_cvt_f16_f32_e32 v100, v100
	v_mul_f32_e32 v108, v108, v177
	v_mul_f32_e32 v108, v234, v108
	global_store_short v[172:173], v96, off offset:352
	v_mul_f32_e32 v96, 0x4b800000, v176
	v_cndmask_b32_e32 v96, v176, v96, vcc
	v_rsq_f32_e32 v96, v96
	v_mul_f32_e32 v108, v235, v108
	v_med3_f32 v108, v108, s57, v194
	global_store_short v[172:173], v100, off offset:320
	v_mul_f32_e32 v100, 0x45800000, v96
	v_cvt_f16_f32_e32 v108, v108
	v_cndmask_b32_e32 v96, v96, v100, vcc
	v_cvt_f32_f16_e32 v100, v230
	v_mul_f32_e32 v104, v104, v177
	v_mul_f32_e32 v104, v233, v104
	global_store_short v[172:173], v108, off offset:256
	v_mul_f32_e32 v104, v242, v104
	v_mul_f32_e32 v108, 0xbfb8aa3b, v100
	v_med3_f32 v104, v104, s57, v194
	v_exp_f32_e32 v108, v108
	v_cvt_f16_f32_e32 v104, v104
	v_mul_f32_e32 v101, v101, v96
	v_mul_f32_e32 v101, v232, v101
	v_add_f32_e32 v108, 1.0, v108
	global_store_short v[172:173], v104, off offset:288
	v_mul_f32_e32 v104, v109, v96
	v_div_scale_f32 v109, s[8:9], v108, v108, v100
	v_rcp_f32_e32 v172, v109
	v_mul_f32_e32 v104, v234, v104
	v_fma_f32 v173, -v109, v172, 1.0
	v_fmac_f32_e32 v172, v173, v172
	v_div_scale_f32 v173, vcc, v100, v108, v100
	v_mul_f32_e32 v176, v173, v172
	v_fma_f32 v177, -v109, v176, v173
	v_fmac_f32_e32 v176, v177, v172
	v_fma_f32 v109, -v109, v176, v173
	v_div_fmas_f32 v109, v109, v172, v176
	v_div_fixup_f32 v100, v109, v108, v100
	v_mul_f32_e32 v100, v100, v104
	v_med3_f32 v100, v100, s57, v194
	v_cvt_f16_f32_e32 v100, v100
	v_mul_f32_e32 v104, v105, v96
	v_mul_f32_e32 v104, v233, v104
	v_mul_f32_e32 v96, v97, v96
	global_store_short v[170:171], v100, off offset:2560
	v_cvt_f32_f16_e32 v100, v229
	v_mul_f32_e32 v96, v231, v96
	v_mul_f32_e32 v105, 0xbfb8aa3b, v100
	v_exp_f32_e32 v105, v105
	s_nop 0
	v_add_f32_e32 v105, 1.0, v105
	v_div_scale_f32 v108, s[8:9], v105, v105, v100
	v_rcp_f32_e32 v109, v108
	s_nop 0
	v_fma_f32 v172, -v108, v109, 1.0
	v_fmac_f32_e32 v109, v172, v109
	v_div_scale_f32 v172, vcc, v100, v105, v100
	v_mul_f32_e32 v173, v172, v109
	v_fma_f32 v176, -v108, v173, v172
	v_fmac_f32_e32 v173, v176, v109
	v_fma_f32 v108, -v108, v173, v172
	v_div_fmas_f32 v108, v108, v109, v173
	v_div_fixup_f32 v100, v108, v105, v100
	v_mul_f32_e32 v100, v100, v104
	v_med3_f32 v100, v100, s57, v194
	v_cvt_f16_f32_e32 v100, v100
	global_store_short v[170:171], v100, off offset:2592
	v_cvt_f32_f16_e32 v100, v228
	v_mul_f32_e32 v104, 0xbfb8aa3b, v100
	v_exp_f32_e32 v104, v104
	s_nop 0
	v_add_f32_e32 v104, 1.0, v104
	v_div_scale_f32 v105, s[8:9], v104, v104, v100
	v_rcp_f32_e32 v108, v105
	s_nop 0
	v_fma_f32 v109, -v105, v108, 1.0
	v_fmac_f32_e32 v108, v109, v108
	v_div_scale_f32 v109, vcc, v100, v104, v100
	v_mul_f32_e32 v172, v109, v108
	v_fma_f32 v173, -v105, v172, v109
	v_fmac_f32_e32 v172, v173, v108
	v_fma_f32 v105, -v105, v172, v109
	v_div_fmas_f32 v105, v105, v108, v172
	v_div_fixup_f32 v100, v105, v104, v100
	v_mul_f32_e32 v100, v100, v101
	v_med3_f32 v100, v100, s57, v194
	v_cvt_f16_f32_e32 v100, v100
	global_store_short v[170:171], v100, off offset:2624
	v_cvt_f32_f16_e32 v100, v227
	v_mul_f32_e32 v97, 0xbfb8aa3b, v100
	v_exp_f32_e32 v97, v97
	s_nop 0
	v_add_f32_e32 v97, 1.0, v97
	v_div_scale_f32 v101, s[8:9], v97, v97, v100
	v_rcp_f32_e32 v104, v101
	s_nop 0
	v_fma_f32 v105, -v101, v104, 1.0
	v_fmac_f32_e32 v104, v105, v104
	v_div_scale_f32 v105, vcc, v100, v97, v100
	v_mul_f32_e32 v108, v105, v104
	v_fma_f32 v109, -v101, v108, v105
	v_fmac_f32_e32 v108, v109, v104
	v_fma_f32 v101, -v101, v108, v105
	v_div_fmas_f32 v101, v101, v104, v108
	v_cvt_f32_f16_e32 v104, v226
	v_div_fixup_f32 v97, v101, v97, v100
	v_mul_f32_e32 v96, v97, v96
	v_med3_f32 v96, v96, s57, v194
	v_mul_f32_e32 v105, 0xbfb8aa3b, v104
	v_exp_f32_e32 v105, v105
	v_cvt_f16_f32_e32 v96, v96
	v_mov_b32_e32 v97, v106
	v_add_f32_e32 v105, 1.0, v105
	v_div_scale_f32 v108, s[8:9], v105, v105, v104
	v_rcp_f32_e32 v109, v108
	global_store_short v[170:171], v96, off offset:2656
	v_mov_b32_e32 v96, v110
	v_mul_f32_e64 v100, v96, v96
	v_mul_f32_e64 v101, v97, v97
	v_fma_f32 v170, -v108, v109, 1.0
	v_fmac_f32_e32 v109, v170, v109
	v_div_scale_f32 v170, vcc, v104, v105, v104
	v_mul_f32_e32 v171, v170, v109
	v_fma_f32 v172, -v108, v171, v170
	v_fmac_f32_e32 v171, v172, v109
	v_fma_f32 v108, -v108, v171, v170
	v_div_fmas_f32 v108, v108, v109, v171
	v_div_fixup_f32 v172, v108, v105, v104
	v_cvt_f32_f16_e32 v104, v225
	v_mov_b32_e32 v96, v102
	v_mov_b32_e32 v97, v98
	v_mul_f32_e64 v96, v96, v96
	v_mul_f32_e64 v97, v97, v97
	v_mul_f32_e32 v105, 0xbfb8aa3b, v104
	v_exp_f32_e32 v105, v105
	s_nop 0
	v_add_f32_e32 v105, 1.0, v105
	v_div_scale_f32 v108, s[8:9], v105, v105, v104
	v_rcp_f32_e32 v109, v108
	s_nop 0
	v_fma_f32 v170, -v108, v109, 1.0
	v_fmac_f32_e32 v109, v170, v109
	v_div_scale_f32 v170, vcc, v104, v105, v104
	v_mul_f32_e32 v171, v170, v109
	v_fma_f32 v173, -v108, v171, v170
	v_fmac_f32_e32 v171, v173, v109
	v_fma_f32 v108, -v108, v171, v170
	v_div_fmas_f32 v108, v108, v109, v171
	v_div_fixup_f32 v173, v108, v105, v104
	v_cvt_f32_f16_e32 v104, v224
	v_mul_f32_e32 v105, 0xbfb8aa3b, v104
	v_exp_f32_e32 v105, v105
	s_nop 0
	v_add_f32_e32 v105, 1.0, v105
	v_div_scale_f32 v108, s[8:9], v105, v105, v104
	v_rcp_f32_e32 v109, v108
	s_nop 0
	v_fma_f32 v170, -v108, v109, 1.0
	v_fmac_f32_e32 v109, v170, v109
	v_div_scale_f32 v170, vcc, v104, v105, v104
	v_mul_f32_e32 v171, v170, v109
	v_fma_f32 v176, -v108, v171, v170
	v_fmac_f32_e32 v171, v176, v109
	v_fma_f32 v108, -v108, v171, v170
	v_div_fmas_f32 v108, v108, v109, v171
	v_div_fixup_f32 v176, v108, v105, v104
	v_cvt_f32_f16_e32 v104, v223
	v_mul_f32_e32 v105, 0xbfb8aa3b, v104
	v_exp_f32_e32 v105, v105
	s_nop 0
	v_add_f32_e32 v105, 1.0, v105
	v_div_scale_f32 v108, s[8:9], v105, v105, v104
	v_rcp_f32_e32 v109, v108
	s_nop 0
	v_fma_f32 v170, -v108, v109, 1.0
	v_fmac_f32_e32 v109, v170, v109
	v_div_scale_f32 v170, vcc, v104, v105, v104
	v_mul_f32_e32 v171, v170, v109
	v_fma_f32 v177, -v108, v171, v170
	v_fmac_f32_e32 v171, v177, v109
	v_fma_f32 v108, -v108, v171, v170
	v_div_fmas_f32 v108, v108, v109, v171
	v_div_fixup_f32 v177, v108, v105, v104
	v_mov_b32_e32 v104, v111
	v_mov_b32_e32 v105, v107
	v_mul_f32_e64 v104, v104, v104
	v_mul_f32_e64 v105, v105, v105
	v_mov_b32_e32 v108, v103
	v_mov_b32_e32 v109, v99
	v_mul_f32_e64 v108, v108, v108
	v_mul_f32_e64 v109, v109, v109
	v_mov_b32_e32 v170, v104
	v_mov_b32_e32 v171, v100
	v_mov_b32_e32 v100, v105
	v_add_f32_e64 v100, v170, v100
	v_add_f32_e64 v101, v171, v101
	v_mov_b32_e32 v104, v108
	v_mov_b32_e32 v105, v96
	v_add_f32_e64 v100, v100, v104
	v_add_f32_e64 v101, v101, v105
	v_mov_b32_e32 v96, v109
	v_add_f32_e64 v96, v100, v96
	v_add_f32_e64 v97, v101, v97
	s_nop 1
	v_mov_b32_dpp v101, v97 quad_perm:[1,0,3,2] row_mask:0xf bank_mask:0xf bound_ctrl:1
	v_mov_b32_dpp v100, v96 quad_perm:[1,0,3,2] row_mask:0xf bank_mask:0xf bound_ctrl:1
	v_add_f32_e64 v96, v96, v100
	v_add_f32_e64 v97, v97, v101
	s_nop 1
	v_mov_b32_dpp v101, v97 quad_perm:[2,3,0,1] row_mask:0xf bank_mask:0xf bound_ctrl:1
	v_mov_b32_dpp v100, v96 quad_perm:[2,3,0,1] row_mask:0xf bank_mask:0xf bound_ctrl:1
	v_add_f32_e64 v96, v96, v100
	v_add_f32_e64 v97, v97, v101
	s_nop 1
	v_mov_b32_dpp v101, v97 row_ror:4 row_mask:0xf bank_mask:0xf bound_ctrl:1
	v_mov_b32_dpp v100, v96 row_ror:4 row_mask:0xf bank_mask:0xf bound_ctrl:1
	v_add_f32_e64 v96, v96, v100
	v_add_f32_e64 v97, v97, v101
	s_nop 1
	v_mov_b32_dpp v101, v97 row_ror:8 row_mask:0xf bank_mask:0xf bound_ctrl:1
	v_mov_b32_dpp v100, v96 row_ror:8 row_mask:0xf bank_mask:0xf bound_ctrl:1
	v_add_f32_e64 v96, v96, v100
	v_add_f32_e64 v97, v97, v101
	s_nop 0
	v_fma_f32 v96, v96, s0, v174
	v_fma_f32 v97, v97, s0, v174
	s_nop 0
	v_mul_f32_e32 v100, 0x4b800000, v97
	v_cmp_gt_f32_e64 s[8:9], s49, v97
	v_cmp_gt_f32_e32 vcc, s49, v96
	s_nop 0
	v_cndmask_b32_e64 v97, v97, v100, s[8:9]
	v_rsq_f32_e32 v97, v97
	s_nop 0
	v_mul_f32_e32 v100, 0x45800000, v97
	v_cndmask_b32_e64 v97, v97, v100, s[8:9]
	v_mul_f32_e32 v100, v110, v97
	v_mul_f32_e32 v100, v234, v100
	v_mul_f32_e32 v100, v172, v100
	v_med3_f32 v100, v100, s57, v194
	v_cvt_f16_f32_e32 v100, v100
	global_store_short v[168:169], v100, off offset:768
	v_mul_f32_e32 v100, v106, v97
	v_mul_f32_e32 v100, v233, v100
	v_mul_f32_e32 v100, v173, v100
	v_med3_f32 v100, v100, s57, v194
	v_cvt_f16_f32_e32 v100, v100
	global_store_short v[168:169], v100, off offset:800
	v_mul_f32_e32 v100, v102, v97
	v_mul_f32_e32 v97, v98, v97
	v_mul_f32_e32 v97, v231, v97
	v_mul_f32_e32 v97, v177, v97
	v_med3_f32 v97, v97, s57, v194
	v_cvt_f16_f32_e32 v97, v97
	v_mul_f32_e32 v100, v232, v100
	v_mul_f32_e32 v100, v176, v100
	v_med3_f32 v100, v100, s57, v194
	global_store_short v[168:169], v97, off offset:864
	v_mul_f32_e32 v97, 0x4b800000, v96
	v_cndmask_b32_e32 v96, v96, v97, vcc
	v_rsq_f32_e32 v96, v96
	v_cvt_f16_f32_e32 v100, v100
	v_mul_f32_e32 v97, 0x45800000, v96
	v_cndmask_b32_e32 v96, v96, v97, vcc
	v_cvt_f32_f16_e32 v97, v181
	global_store_short v[168:169], v100, off offset:832
	v_mul_f32_e32 v98, v111, v96
	v_mul_f32_e32 v98, v234, v98
	v_mul_f32_e32 v100, 0xbfb8aa3b, v97
	v_exp_f32_e32 v100, v100
	s_nop 0
	v_add_f32_e32 v100, 1.0, v100
	v_div_scale_f32 v101, s[8:9], v100, v100, v97
	v_rcp_f32_e32 v102, v101
	s_nop 0
	v_fma_f32 v104, -v101, v102, 1.0
	v_fmac_f32_e32 v102, v104, v102
	v_div_scale_f32 v104, vcc, v97, v100, v97
	v_mul_f32_e32 v105, v104, v102
	v_fma_f32 v106, -v101, v105, v104
	v_fmac_f32_e32 v105, v106, v102
	v_fma_f32 v101, -v101, v105, v104
	v_div_fmas_f32 v101, v101, v102, v105
	v_div_fixup_f32 v97, v101, v100, v97
	v_mul_f32_e32 v97, v97, v98
	v_med3_f32 v97, v97, s57, v194
	v_cvt_f16_f32_e32 v97, v97
	v_mul_f32_e32 v98, v107, v96
	v_mul_f32_e32 v98, v233, v98
	global_store_short v[166:167], v97, off offset:3072
	v_cvt_f32_f16_e32 v97, v180
	v_mul_f32_e32 v100, 0xbfb8aa3b, v97
	v_exp_f32_e32 v100, v100
	s_nop 0
	v_add_f32_e32 v100, 1.0, v100
	v_div_scale_f32 v101, s[8:9], v100, v100, v97
	v_rcp_f32_e32 v102, v101
	s_nop 0
	v_fma_f32 v104, -v101, v102, 1.0
	v_fmac_f32_e32 v102, v104, v102
	v_div_scale_f32 v104, vcc, v97, v100, v97
	v_mul_f32_e32 v105, v104, v102
	v_fma_f32 v106, -v101, v105, v104
	v_fmac_f32_e32 v105, v106, v102
	v_fma_f32 v101, -v101, v105, v104
	v_div_fmas_f32 v101, v101, v102, v105
	v_div_fixup_f32 v97, v101, v100, v97
	v_mul_f32_e32 v97, v97, v98
	v_med3_f32 v97, v97, s57, v194
	v_cvt_f16_f32_e32 v97, v97
	v_mul_f32_e32 v98, v103, v96
	v_mul_f32_e32 v98, v232, v98
	v_mul_f32_e32 v96, v99, v96
	global_store_short v[166:167], v97, off offset:3104
	v_cvt_f32_f16_e32 v97, v179
	v_mul_f32_e32 v96, v231, v96
	v_mul_f32_e32 v100, 0xbfb8aa3b, v97
	v_exp_f32_e32 v100, v100
	s_nop 0
	v_add_f32_e32 v100, 1.0, v100
	v_div_scale_f32 v101, s[8:9], v100, v100, v97
	v_rcp_f32_e32 v102, v101
	s_nop 0
	v_fma_f32 v103, -v101, v102, 1.0
	v_fmac_f32_e32 v102, v103, v102
	v_div_scale_f32 v103, vcc, v97, v100, v97
	v_mul_f32_e32 v104, v103, v102
	v_fma_f32 v105, -v101, v104, v103
	v_fmac_f32_e32 v104, v105, v102
	v_fma_f32 v101, -v101, v104, v103
	v_div_fmas_f32 v101, v101, v102, v104
	v_div_fixup_f32 v97, v101, v100, v97
	v_mul_f32_e32 v97, v97, v98
	v_med3_f32 v97, v97, s57, v194
	v_cvt_f16_f32_e32 v97, v97
	global_store_short v[166:167], v97, off offset:3136
	v_cvt_f32_f16_e32 v97, v178
	v_mul_f32_e32 v98, 0xbfb8aa3b, v97
	v_exp_f32_e32 v98, v98
	s_nop 0
	v_add_f32_e32 v98, 1.0, v98
	v_div_scale_f32 v99, s[8:9], v98, v98, v97
	v_rcp_f32_e32 v100, v99
	s_nop 0
	v_fma_f32 v101, -v99, v100, 1.0
	v_fmac_f32_e32 v100, v101, v100
	v_div_scale_f32 v101, vcc, v97, v98, v97
	v_mul_f32_e32 v102, v101, v100
	v_fma_f32 v103, -v99, v102, v101
	v_fmac_f32_e32 v102, v103, v100
	v_fma_f32 v99, -v99, v102, v101
	v_div_fmas_f32 v99, v99, v100, v102
	v_div_fixup_f32 v97, v99, v98, v97
	v_mul_f32_e32 v96, v97, v96
	v_med3_f32 v96, v96, s57, v194
	v_cvt_f16_f32_e32 v96, v96
	s_andn2_b64 vcc, exec, s[10:11]
	global_store_short v[166:167], v96, off offset:3168
	ds_read_b128 v[96:99], v116 offset:55296
	ds_read_b128 v[240:243], v117 offset:36864
	ds_read_b128 v[244:247], v117 offset:39168
	ds_read_b128 v[252:255], v117 offset:41472
	s_waitcnt lgkmcnt(2)
	v_mul_f32_e64 v82, v82, v112
	v_mul_f32_e64 v83, v83, v112
	v_mul_f32_e64 v80, v80, v112
	v_mul_f32_e64 v81, v81, v112
	v_mul_f32_e64 v86, v86, v112
	v_mul_f32_e64 v87, v87, v112
	v_mul_f32_e64 v84, v84, v112
	v_mul_f32_e64 v85, v85, v112
	v_mul_f32_e64 v90, v90, v112
	v_mul_f32_e64 v91, v91, v112
	v_mul_f32_e64 v88, v88, v112
	v_mul_f32_e64 v89, v89, v112
	v_mul_f32_e64 v94, v94, v112
	v_mul_f32_e64 v95, v95, v112
	v_mul_f32_e64 v92, v92, v112
	v_mul_f32_e64 v93, v93, v112
	s_nop 1
	v_mfma_f32_16x16x32_f16 v[80:83], v[96:99], v[240:243], v[80:83]
	ds_read_b128 v[240:243], v117 offset:43776
	ds_read_b128 v[100:103], v116 offset:55360
	s_waitcnt lgkmcnt(3)
	v_mfma_f32_16x16x32_f16 v[84:87], v[96:99], v[244:247], v[84:87]
	ds_read_b128 v[244:247], v117 offset:36928
	s_waitcnt lgkmcnt(3)
	v_mfma_f32_16x16x32_f16 v[88:91], v[96:99], v[252:255], v[88:91]
	ds_read_b128 v[252:255], v117 offset:39232
	s_waitcnt lgkmcnt(3)
	v_mfma_f32_16x16x32_f16 v[92:95], v[96:99], v[240:243], v[92:95]
	ds_read_b128 v[240:243], v117 offset:41536
	s_waitcnt lgkmcnt(2)
	v_mfma_f32_16x16x32_f16 v[80:83], v[100:103], v[244:247], v[80:83]
	ds_read_b128 v[244:247], v117 offset:43840
	s_waitcnt lgkmcnt(2)
	v_mfma_f32_16x16x32_f16 v[84:87], v[100:103], v[252:255], v[84:87]
	s_waitcnt lgkmcnt(1)
	v_mfma_f32_16x16x32_f16 v[88:91], v[100:103], v[240:243], v[88:91]
	s_waitcnt lgkmcnt(0)
	s_barrier
	v_mfma_f32_16x16x32_f16 v[92:95], v[100:103], v[244:247], v[92:95]
	v_max_f32_e32 v96, v80, v80
	v_med3_f32 v96, v96, s57, v194
	v_cvt_f16_f32_e32 v96, v96
	ds_write_b16 v215, v96 offset:46080
	v_max_f32_e32 v96, v81, v81
	v_med3_f32 v96, v96, s57, v194
	v_cvt_f16_f32_e32 v96, v96
	ds_write_b16 v215, v96 offset:46224
	v_max_f32_e32 v96, v82, v82
	v_med3_f32 v96, v96, s57, v194
	v_cvt_f16_f32_e32 v96, v96
	ds_write_b16 v215, v96 offset:46368
	v_max_f32_e32 v96, v83, v83
	v_med3_f32 v96, v96, s57, v194
	v_cvt_f16_f32_e32 v96, v96
	ds_write_b16 v215, v96 offset:46512
	v_max_f32_e32 v96, v84, v84
	v_med3_f32 v96, v96, s57, v194
	v_cvt_f16_f32_e32 v96, v96
	ds_write_b16 v215, v96 offset:46112
	v_max_f32_e32 v96, v85, v85
	v_med3_f32 v96, v96, s57, v194
	v_cvt_f16_f32_e32 v96, v96
	ds_write_b16 v216, v96 offset:46224
	v_max_f32_e32 v96, v86, v86
	v_med3_f32 v96, v96, s57, v194
	v_cvt_f16_f32_e32 v96, v96
	ds_write_b16 v216, v96 offset:46368
	v_max_f32_e32 v96, v87, v87
	v_med3_f32 v96, v96, s57, v194
	v_cvt_f16_f32_e32 v96, v96
	ds_write_b16 v216, v96 offset:46512
	v_max_f32_e32 v96, v88, v88
	v_med3_f32 v96, v96, s57, v194
	v_cvt_f16_f32_e32 v96, v96
	ds_write_b16 v215, v96 offset:46144
	v_max_f32_e32 v96, v89, v89
	v_med3_f32 v96, v96, s57, v194
	v_cvt_f16_f32_e32 v96, v96
	ds_write_b16 v217, v96 offset:46224
	v_max_f32_e32 v96, v90, v90
	v_med3_f32 v96, v96, s57, v194
	v_cvt_f16_f32_e32 v96, v96
	ds_write_b16 v217, v96 offset:46368
	v_max_f32_e32 v96, v91, v91
	v_med3_f32 v96, v96, s57, v194
	v_cvt_f16_f32_e32 v96, v96
	ds_write_b16 v217, v96 offset:46512
	v_max_f32_e32 v96, v92, v92
	v_med3_f32 v96, v96, s57, v194
	v_cvt_f16_f32_e32 v96, v96
	ds_write_b16 v215, v96 offset:46176
	v_max_f32_e32 v96, v93, v93
	v_med3_f32 v96, v96, s57, v194
	v_cvt_f16_f32_e32 v96, v96
	ds_write_b16 v218, v96 offset:46224
	v_max_f32_e32 v96, v94, v94
	v_med3_f32 v96, v96, s57, v194
	v_cvt_f16_f32_e32 v96, v96
	ds_write_b16 v218, v96 offset:46368
	v_max_f32_e32 v96, v95, v95
	v_med3_f32 v96, v96, s57, v194
	v_cvt_f16_f32_e32 v96, v96
	ds_write_b16 v218, v96 offset:46512
	ds_write_b128 v220, v[16:19]
	ds_write_b128 v211, v[20:23]
	ds_write_b128 v221, v[24:27]
	ds_write_b128 v212, v[28:31]
	ds_write_b128 v222, v[32:35]
	ds_write_b128 v213, v[36:39]
	s_waitcnt lgkmcnt(0)

.LBB0_527:
	s_mov_b64 s[8:9], 0x65100
	v_lshl_add_u64 v[178:179], v[108:109], 0, s[8:9]
	s_mov_b64 s[8:9], 0x65120
	v_lshl_add_u64 v[176:177], v[108:109], 0, s[8:9]
	s_mov_b64 s[8:9], 0x65140
	v_lshl_add_u64 v[174:175], v[108:109], 0, s[8:9]
	s_mov_b64 s[8:9], 0x65160
	v_lshl_add_u64 v[172:173], v[108:109], 0, s[8:9]
	s_mov_b64 s[8:9], 0x66a00
	v_lshl_add_u64 v[168:169], v[108:109], 0, s[8:9]
	s_mov_b64 s[8:9], 0x66a20
	v_lshl_add_u64 v[166:167], v[108:109], 0, s[8:9]
	s_mov_b64 s[8:9], 0x66a40
	v_lshl_add_u64 v[164:165], v[108:109], 0, s[8:9]
	s_mov_b64 s[8:9], 0x66a60
	v_lshl_add_u64 v[162:163], v[108:109], 0, s[8:9]
	s_mov_b64 s[8:9], 0x68300
	v_lshl_add_u64 v[160:161], v[108:109], 0, s[8:9]
	s_mov_b64 s[8:9], 0x68320
	v_lshl_add_u64 v[158:159], v[108:109], 0, s[8:9]
	s_mov_b64 s[8:9], 0x68340
	v_lshl_add_u64 v[156:157], v[108:109], 0, s[8:9]
	s_mov_b64 s[8:9], 0x68360
	v_lshl_add_u64 v[154:155], v[108:109], 0, s[8:9]
	s_mov_b64 s[8:9], 0x69c00
	v_lshl_add_u64 v[152:153], v[108:109], 0, s[8:9]
	s_mov_b64 s[8:9], 0x69c20
	v_lshl_add_u64 v[150:151], v[108:109], 0, s[8:9]
	s_mov_b64 s[8:9], 0x69c40
	v_lshl_add_u64 v[148:149], v[108:109], 0, s[8:9]
	s_mov_b64 s[8:9], 0x69c60
	v_lshl_add_u64 v[146:147], v[108:109], 0, s[8:9]
	s_waitcnt vmcnt(15)
	v_cvt_f32_f16_e32 v239, v238
	s_mov_b32 s0, 0x358637bd
	global_load_dword v238, v[118:119], off
	ds_read_b128 v[240:243], v116 offset:27648
	ds_read_b128 v[244:247], v117 offset:46080
	ds_read_b128 v[252:255], v117 offset:48384
	s_waitcnt lgkmcnt(1)
	v_mfma_f32_16x16x32_f16 v[108:111], v[240:243], v[244:247], 0
	ds_read_b128 v[244:247], v117 offset:50688
	s_waitcnt lgkmcnt(1)
	v_mfma_f32_16x16x32_f16 v[104:107], v[240:243], v[252:255], 0
	ds_read_b128 v[252:255], v117 offset:52992
	s_waitcnt lgkmcnt(1)
	v_mfma_f32_16x16x32_f16 v[100:103], v[240:243], v[244:247], 0
	s_waitcnt lgkmcnt(0)
	v_mfma_f32_16x16x32_f16 v[96:99], v[240:243], v[252:255], 0
	ds_read_b128 v[240:243], v116 offset:27712
	ds_read_b128 v[244:247], v117 offset:46144
	ds_read_b128 v[252:255], v117 offset:48448
	s_waitcnt lgkmcnt(1)
	v_mfma_f32_16x16x32_f16 v[108:111], v[240:243], v[244:247], v[108:111]
	ds_read_b128 v[244:247], v117 offset:50752
	s_waitcnt lgkmcnt(1)
	v_mfma_f32_16x16x32_f16 v[104:107], v[240:243], v[252:255], v[104:107]
	ds_read_b128 v[252:255], v117 offset:53056
	s_waitcnt lgkmcnt(1)
	v_mfma_f32_16x16x32_f16 v[100:103], v[240:243], v[244:247], v[100:103]
	s_waitcnt lgkmcnt(0)
	v_mfma_f32_16x16x32_f16 v[96:99], v[240:243], v[252:255], v[96:99]
	ds_read_b128 v[240:243], v116 offset:18432
	ds_read_b128 v[244:247], v117 offset:55296
	ds_read_b128 v[252:255], v117 offset:57600
	s_waitcnt lgkmcnt(1)
	v_mfma_f32_16x16x32_f16 v[108:111], v[240:243], v[244:247], v[108:111]
	ds_read_b128 v[244:247], v117 offset:59904
	s_waitcnt lgkmcnt(1)
	v_mfma_f32_16x16x32_f16 v[104:107], v[240:243], v[252:255], v[104:107]
	ds_read_b128 v[252:255], v117 offset:62208
	s_waitcnt lgkmcnt(1)
	v_mfma_f32_16x16x32_f16 v[100:103], v[240:243], v[244:247], v[100:103]
	s_waitcnt lgkmcnt(0)
	v_mfma_f32_16x16x32_f16 v[96:99], v[240:243], v[252:255], v[96:99]
	ds_read_b128 v[240:243], v116 offset:18496
	ds_read_b128 v[244:247], v117 offset:55360
	ds_read_b128 v[252:255], v117 offset:57664
	s_waitcnt lgkmcnt(1)
	v_mfma_f32_16x16x32_f16 v[108:111], v[240:243], v[244:247], v[108:111]
	ds_read_b128 v[244:247], v117 offset:59968
	s_waitcnt lgkmcnt(1)
	v_mfma_f32_16x16x32_f16 v[104:107], v[240:243], v[252:255], v[104:107]
	s_nop 7
	v_mov_b32_e32 v170, v108
	v_mov_b32_e32 v171, v104
	ds_read_b128 v[252:255], v117 offset:62272
	s_waitcnt lgkmcnt(1)
	v_mfma_f32_16x16x32_f16 v[100:103], v[240:243], v[244:247], v[100:103]
	s_nop 7
	v_mul_f32_e64 v180, v170, v170
	v_mul_f32_e64 v181, v171, v171
	s_waitcnt lgkmcnt(0)
	v_mfma_f32_16x16x32_f16 v[96:99], v[240:243], v[252:255], v[96:99]
	v_mul_f32_e32 v240, 0xbfb8aa3b, v239
	v_exp_f32_e32 v240, v240
	v_mov_b32_e32 v170, v100
	s_nop 4
	v_mov_b32_e32 v171, v96
	v_mul_f32_e64 v170, v170, v170
	v_mul_f32_e64 v171, v171, v171
	v_add_f32_e32 v240, 1.0, v240
	v_div_scale_f32 v241, s[8:9], v240, v240, v239
	v_rcp_f32_e32 v242, v241
	s_nop 0
	v_fma_f32 v243, -v241, v242, 1.0
	v_fmac_f32_e32 v242, v243, v242
	v_div_scale_f32 v243, vcc, v239, v240, v239
	v_mul_f32_e32 v244, v243, v242
	v_fma_f32 v245, -v241, v244, v243
	v_fmac_f32_e32 v244, v245, v242
	v_fma_f32 v241, -v241, v244, v243
	v_div_fmas_f32 v241, v241, v242, v244
	v_div_fixup_f32 v239, v241, v240, v239
	s_waitcnt vmcnt(15)
	v_cvt_f32_f16_e32 v240, v237
	global_load_dword v237, v[118:119], off offset:64
	v_mul_f32_e32 v241, 0xbfb8aa3b, v240
	v_exp_f32_e32 v241, v241
	s_nop 0
	v_add_f32_e32 v241, 1.0, v241
	v_div_scale_f32 v242, s[8:9], v241, v241, v240
	v_rcp_f32_e32 v243, v242
	s_nop 0
	v_fma_f32 v244, -v242, v243, 1.0
	v_fmac_f32_e32 v243, v244, v243
	v_div_scale_f32 v244, vcc, v240, v241, v240
	v_mul_f32_e32 v245, v244, v243
	v_fma_f32 v246, -v242, v245, v244
	v_fmac_f32_e32 v245, v246, v243
	v_fma_f32 v242, -v242, v245, v244
	v_div_fmas_f32 v242, v242, v243, v245
	v_div_fixup_f32 v246, v242, v241, v240
	s_waitcnt vmcnt(15)
	v_cvt_f32_f16_e32 v240, v236
	global_load_dword v236, v[118:119], off offset:128
	v_mul_f32_e32 v241, 0xbfb8aa3b, v240
	v_exp_f32_e32 v241, v241
	s_nop 0
	v_add_f32_e32 v241, 1.0, v241
	v_div_scale_f32 v242, s[8:9], v241, v241, v240
	v_rcp_f32_e32 v243, v242
	s_nop 0
	v_fma_f32 v244, -v242, v243, 1.0
	v_fmac_f32_e32 v243, v244, v243
	v_div_scale_f32 v244, vcc, v240, v241, v240
	v_mul_f32_e32 v245, v244, v243
	v_fma_f32 v247, -v242, v245, v244
	v_fmac_f32_e32 v245, v247, v243
	v_fma_f32 v242, -v242, v245, v244
	v_div_fmas_f32 v242, v242, v243, v245
	v_div_fixup_f32 v247, v242, v241, v240
	s_waitcnt vmcnt(15)
	v_cvt_f32_f16_e32 v240, v235
	global_load_dword v235, v[118:119], off offset:192
	v_mul_f32_e32 v241, 0xbfb8aa3b, v240
	v_exp_f32_e32 v241, v241
	s_nop 0
	v_add_f32_e32 v241, 1.0, v241
	v_div_scale_f32 v242, s[8:9], v241, v241, v240
	v_rcp_f32_e32 v243, v242
	s_nop 0
	v_fma_f32 v244, -v242, v243, 1.0
	v_fmac_f32_e32 v243, v244, v243
	v_div_scale_f32 v244, vcc, v240, v241, v240
	v_mul_f32_e32 v245, v244, v243
	v_fma_f32 v248, -v242, v245, v244
	v_fmac_f32_e32 v245, v248, v243
	v_fma_f32 v242, -v242, v245, v244
	v_div_fmas_f32 v242, v242, v243, v245
	v_div_fixup_f32 v248, v242, v241, v240
	v_mov_b32_e32 v240, v109
	v_mov_b32_e32 v241, v105
	v_mul_f32_e64 v240, v240, v240
	v_mul_f32_e64 v241, v241, v241
	v_mov_b32_e32 v242, v101
	v_mov_b32_e32 v243, v97
	v_mul_f32_e64 v242, v242, v242
	v_mul_f32_e64 v243, v243, v243
	v_mov_b32_e32 v244, v240
	v_mov_b32_e32 v245, v180
	v_mov_b32_e32 v180, v241
	v_add_f32_e64 v180, v244, v180
	v_add_f32_e64 v181, v245, v181
	v_mov_b32_e32 v240, v242
	v_mov_b32_e32 v241, v170
	v_add_f32_e64 v180, v180, v240
	v_add_f32_e64 v181, v181, v241
	v_mov_b32_e32 v170, v243
	v_add_f32_e64 v170, v180, v170
	v_add_f32_e64 v171, v181, v171
	s_nop 1
	v_mov_b32_dpp v181, v171 quad_perm:[1,0,3,2] row_mask:0xf bank_mask:0xf bound_ctrl:1
	v_mov_b32_dpp v180, v170 quad_perm:[1,0,3,2] row_mask:0xf bank_mask:0xf bound_ctrl:1
	v_add_f32_e64 v170, v170, v180
	v_add_f32_e64 v171, v171, v181
	s_nop 1
	v_mov_b32_dpp v181, v171 quad_perm:[2,3,0,1] row_mask:0xf bank_mask:0xf bound_ctrl:1
	v_mov_b32_dpp v180, v170 quad_perm:[2,3,0,1] row_mask:0xf bank_mask:0xf bound_ctrl:1
	v_add_f32_e64 v170, v170, v180
	v_add_f32_e64 v171, v171, v181
	s_nop 1
	v_mov_b32_dpp v181, v171 row_ror:4 row_mask:0xf bank_mask:0xf bound_ctrl:1
	v_mov_b32_dpp v180, v170 row_ror:4 row_mask:0xf bank_mask:0xf bound_ctrl:1
	v_add_f32_e64 v170, v170, v180
	v_add_f32_e64 v171, v171, v181
	s_nop 1
	v_mov_b32_dpp v181, v171 row_ror:8 row_mask:0xf bank_mask:0xf bound_ctrl:1
	v_mov_b32_dpp v180, v170 row_ror:8 row_mask:0xf bank_mask:0xf bound_ctrl:1
	v_add_f32_e64 v180, v170, v180
	v_add_f32_e64 v181, v171, v181
	v_mov_b64_e32 v[170:171], s[0:1]
	s_mov_b32 s0, 0x3c800000
	v_fma_f32 v180, v180, s0, v170
	v_fma_f32 v181, v181, s0, v170
	s_nop 0
	v_mul_f32_e32 v240, 0x4b800000, v181
	v_cmp_gt_f32_e64 s[8:9], s49, v181
	v_cmp_gt_f32_e32 vcc, s49, v180
	s_nop 0
	v_cndmask_b32_e64 v181, v181, v240, s[8:9]
	v_rsq_f32_e32 v181, v181
	s_nop 0
	v_mul_f32_e32 v240, 0x45800000, v181
	v_cndmask_b32_e64 v181, v181, v240, s[8:9]
	v_mul_f32_e32 v96, v96, v181
	v_mul_f32_e32 v100, v100, v181
	s_waitcnt vmcnt(1)
	v_mul_f32_e32 v100, v236, v100
	v_mul_f32_e32 v100, v247, v100
	v_med3_f32 v100, v100, s57, v194
	s_waitcnt vmcnt(0)
	v_mul_f32_e32 v96, v235, v96
	v_mul_f32_e32 v96, v248, v96
	v_med3_f32 v96, v96, s57, v194
	v_cvt_f16_f32_e32 v96, v96
	v_cvt_f16_f32_e32 v100, v100
	v_mul_f32_e32 v108, v108, v181
	v_mul_f32_e32 v108, v238, v108
	global_store_short v[172:173], v96, off
	v_mul_f32_e32 v96, 0x4b800000, v180
	v_cndmask_b32_e32 v96, v180, v96, vcc
	v_rsq_f32_e32 v96, v96
	v_mul_f32_e32 v108, v239, v108
	v_med3_f32 v108, v108, s57, v194
	global_store_short v[174:175], v100, off
	v_mul_f32_e32 v100, 0x45800000, v96
	v_cvt_f16_f32_e32 v108, v108
	v_cndmask_b32_e32 v96, v96, v100, vcc
	v_cvt_f32_f16_e32 v100, v234
	v_mul_f32_e32 v104, v104, v181
	v_mul_f32_e32 v104, v237, v104
	global_store_short v[178:179], v108, off
	v_mul_f32_e32 v104, v246, v104
	v_mul_f32_e32 v108, 0xbfb8aa3b, v100
	v_med3_f32 v104, v104, s57, v194
	v_exp_f32_e32 v108, v108
	v_cvt_f16_f32_e32 v104, v104
	v_mul_f32_e32 v101, v101, v96
	v_mul_f32_e32 v101, v236, v101
	v_add_f32_e32 v108, 1.0, v108
	global_store_short v[176:177], v104, off
	v_mul_f32_e32 v104, v109, v96
	v_div_scale_f32 v109, s[8:9], v108, v108, v100
	v_rcp_f32_e32 v172, v109
	v_mul_f32_e32 v104, v238, v104
	v_fma_f32 v173, -v109, v172, 1.0
	v_fmac_f32_e32 v172, v173, v172
	v_div_scale_f32 v173, vcc, v100, v108, v100
	v_mul_f32_e32 v174, v173, v172
	v_fma_f32 v175, -v109, v174, v173
	v_fmac_f32_e32 v174, v175, v172
	v_fma_f32 v109, -v109, v174, v173
	v_div_fmas_f32 v109, v109, v172, v174
	v_div_fixup_f32 v100, v109, v108, v100
	v_mul_f32_e32 v100, v100, v104
	v_med3_f32 v100, v100, s57, v194
	v_cvt_f16_f32_e32 v100, v100
	v_mul_f32_e32 v104, v105, v96
	v_mul_f32_e32 v104, v237, v104
	v_mul_f32_e32 v96, v97, v96
	global_store_short v[168:169], v100, off
	v_cvt_f32_f16_e32 v100, v233
	v_mul_f32_e32 v96, v235, v96
	v_mul_f32_e32 v105, 0xbfb8aa3b, v100
	v_exp_f32_e32 v105, v105
	s_nop 0
	v_add_f32_e32 v105, 1.0, v105
	v_div_scale_f32 v108, s[8:9], v105, v105, v100
	v_rcp_f32_e32 v109, v108
	s_nop 0
	v_fma_f32 v168, -v108, v109, 1.0
	v_fmac_f32_e32 v109, v168, v109
	v_div_scale_f32 v168, vcc, v100, v105, v100
	v_mul_f32_e32 v169, v168, v109
	v_fma_f32 v172, -v108, v169, v168
	v_fmac_f32_e32 v169, v172, v109
	v_fma_f32 v108, -v108, v169, v168
	v_div_fmas_f32 v108, v108, v109, v169
	v_div_fixup_f32 v100, v108, v105, v100
	v_mul_f32_e32 v100, v100, v104
	v_med3_f32 v100, v100, s57, v194
	v_cvt_f16_f32_e32 v100, v100
	global_store_short v[166:167], v100, off
	v_cvt_f32_f16_e32 v100, v232
	v_mul_f32_e32 v104, 0xbfb8aa3b, v100
	v_exp_f32_e32 v104, v104
	s_nop 0
	v_add_f32_e32 v104, 1.0, v104
	v_div_scale_f32 v105, s[8:9], v104, v104, v100
	v_rcp_f32_e32 v108, v105
	s_nop 0
	v_fma_f32 v109, -v105, v108, 1.0
	v_fmac_f32_e32 v108, v109, v108
	v_div_scale_f32 v109, vcc, v100, v104, v100
	v_mul_f32_e32 v166, v109, v108
	v_fma_f32 v167, -v105, v166, v109
	v_fmac_f32_e32 v166, v167, v108
	v_fma_f32 v105, -v105, v166, v109
	v_div_fmas_f32 v105, v105, v108, v166
	v_div_fixup_f32 v100, v105, v104, v100
	v_mul_f32_e32 v100, v100, v101
	v_med3_f32 v100, v100, s57, v194
	v_cvt_f16_f32_e32 v100, v100
	global_store_short v[164:165], v100, off
	v_cvt_f32_f16_e32 v100, v231
	v_mul_f32_e32 v97, 0xbfb8aa3b, v100
	v_exp_f32_e32 v97, v97
	s_nop 0
	v_add_f32_e32 v97, 1.0, v97
	v_div_scale_f32 v101, s[8:9], v97, v97, v100
	v_rcp_f32_e32 v104, v101
	s_nop 0
	v_fma_f32 v105, -v101, v104, 1.0
	v_fmac_f32_e32 v104, v105, v104
	v_div_scale_f32 v105, vcc, v100, v97, v100
	v_mul_f32_e32 v108, v105, v104
	v_fma_f32 v109, -v101, v108, v105
	v_fmac_f32_e32 v108, v109, v104
	v_fma_f32 v101, -v101, v108, v105
	v_div_fmas_f32 v101, v101, v104, v108
	v_cvt_f32_f16_e32 v104, v230
	v_div_fixup_f32 v97, v101, v97, v100
	v_mul_f32_e32 v96, v97, v96
	v_med3_f32 v96, v96, s57, v194
	v_mul_f32_e32 v105, 0xbfb8aa3b, v104
	v_exp_f32_e32 v105, v105
	v_cvt_f16_f32_e32 v96, v96
	v_mov_b32_e32 v97, v106
	v_add_f32_e32 v105, 1.0, v105
	v_div_scale_f32 v108, s[8:9], v105, v105, v104
	v_rcp_f32_e32 v109, v108
	global_store_short v[162:163], v96, off
	v_mov_b32_e32 v96, v110
	v_mul_f32_e64 v100, v96, v96
	v_mul_f32_e64 v101, v97, v97
	v_fma_f32 v162, -v108, v109, 1.0
	v_fmac_f32_e32 v109, v162, v109
	v_div_scale_f32 v162, vcc, v104, v105, v104
	v_mul_f32_e32 v163, v162, v109
	v_fma_f32 v164, -v108, v163, v162
	v_fmac_f32_e32 v163, v164, v109
	v_fma_f32 v108, -v108, v163, v162
	v_div_fmas_f32 v108, v108, v109, v163
	v_div_fixup_f32 v164, v108, v105, v104
	v_cvt_f32_f16_e32 v104, v229
	v_mov_b32_e32 v96, v102
	v_mov_b32_e32 v97, v98
	v_mul_f32_e64 v96, v96, v96
	v_mul_f32_e64 v97, v97, v97
	v_mul_f32_e32 v105, 0xbfb8aa3b, v104
	v_exp_f32_e32 v105, v105
	s_nop 0
	v_add_f32_e32 v105, 1.0, v105
	v_div_scale_f32 v108, s[8:9], v105, v105, v104
	v_rcp_f32_e32 v109, v108
	s_nop 0
	v_fma_f32 v162, -v108, v109, 1.0
	v_fmac_f32_e32 v109, v162, v109
	v_div_scale_f32 v162, vcc, v104, v105, v104
	v_mul_f32_e32 v163, v162, v109
	v_fma_f32 v165, -v108, v163, v162
	v_fmac_f32_e32 v163, v165, v109
	v_fma_f32 v108, -v108, v163, v162
	v_div_fmas_f32 v108, v108, v109, v163
	v_div_fixup_f32 v165, v108, v105, v104
	v_cvt_f32_f16_e32 v104, v228
	v_mul_f32_e32 v105, 0xbfb8aa3b, v104
	v_exp_f32_e32 v105, v105
	s_nop 0
	v_add_f32_e32 v105, 1.0, v105
	v_div_scale_f32 v108, s[8:9], v105, v105, v104
	v_rcp_f32_e32 v109, v108
	s_nop 0
	v_fma_f32 v162, -v108, v109, 1.0
	v_fmac_f32_e32 v109, v162, v109
	v_div_scale_f32 v162, vcc, v104, v105, v104
	v_mul_f32_e32 v163, v162, v109
	v_fma_f32 v166, -v108, v163, v162
	v_fmac_f32_e32 v163, v166, v109
	v_fma_f32 v108, -v108, v163, v162
	v_div_fmas_f32 v108, v108, v109, v163
	v_div_fixup_f32 v166, v108, v105, v104
	v_cvt_f32_f16_e32 v104, v227
	v_mul_f32_e32 v105, 0xbfb8aa3b, v104
	v_exp_f32_e32 v105, v105
	s_nop 0
	v_add_f32_e32 v105, 1.0, v105
	v_div_scale_f32 v108, s[8:9], v105, v105, v104
	v_rcp_f32_e32 v109, v108
	s_nop 0
	v_fma_f32 v162, -v108, v109, 1.0
	v_fmac_f32_e32 v109, v162, v109
	v_div_scale_f32 v162, vcc, v104, v105, v104
	v_mul_f32_e32 v163, v162, v109
	v_fma_f32 v167, -v108, v163, v162
	v_fmac_f32_e32 v163, v167, v109
	v_fma_f32 v108, -v108, v163, v162
	v_div_fmas_f32 v108, v108, v109, v163
	v_div_fixup_f32 v167, v108, v105, v104
	v_mov_b32_e32 v104, v111
	v_mov_b32_e32 v105, v107
	v_mul_f32_e64 v104, v104, v104
	v_mul_f32_e64 v105, v105, v105
	v_mov_b32_e32 v108, v103
	v_mov_b32_e32 v109, v99
	v_mul_f32_e64 v108, v108, v108
	v_mul_f32_e64 v109, v109, v109
	v_mov_b32_e32 v162, v104
	v_mov_b32_e32 v163, v100
	v_mov_b32_e32 v100, v105
	v_add_f32_e64 v100, v162, v100
	v_add_f32_e64 v101, v163, v101
	v_mov_b32_e32 v104, v108
	v_mov_b32_e32 v105, v96
	v_add_f32_e64 v100, v100, v104
	v_add_f32_e64 v101, v101, v105
	v_mov_b32_e32 v96, v109
	v_add_f32_e64 v96, v100, v96
	v_add_f32_e64 v97, v101, v97
	s_nop 1
	v_mov_b32_dpp v101, v97 quad_perm:[1,0,3,2] row_mask:0xf bank_mask:0xf bound_ctrl:1
	v_mov_b32_dpp v100, v96 quad_perm:[1,0,3,2] row_mask:0xf bank_mask:0xf bound_ctrl:1
	v_add_f32_e64 v96, v96, v100
	v_add_f32_e64 v97, v97, v101
	s_nop 1
	v_mov_b32_dpp v101, v97 quad_perm:[2,3,0,1] row_mask:0xf bank_mask:0xf bound_ctrl:1
	v_mov_b32_dpp v100, v96 quad_perm:[2,3,0,1] row_mask:0xf bank_mask:0xf bound_ctrl:1
	v_add_f32_e64 v96, v96, v100
	v_add_f32_e64 v97, v97, v101
	s_nop 1
	v_mov_b32_dpp v101, v97 row_ror:4 row_mask:0xf bank_mask:0xf bound_ctrl:1
	v_mov_b32_dpp v100, v96 row_ror:4 row_mask:0xf bank_mask:0xf bound_ctrl:1
	v_add_f32_e64 v96, v96, v100
	v_add_f32_e64 v97, v97, v101
	s_nop 1
	v_mov_b32_dpp v101, v97 row_ror:8 row_mask:0xf bank_mask:0xf bound_ctrl:1
	v_mov_b32_dpp v100, v96 row_ror:8 row_mask:0xf bank_mask:0xf bound_ctrl:1
	v_add_f32_e64 v96, v96, v100
	v_add_f32_e64 v97, v97, v101
	s_nop 0
	v_fma_f32 v96, v96, s0, v170
	v_fma_f32 v97, v97, s0, v170
	s_nop 0
	v_mul_f32_e32 v100, 0x4b800000, v97
	v_cmp_gt_f32_e64 s[8:9], s49, v97
	v_cmp_gt_f32_e32 vcc, s49, v96
	s_nop 0
	v_cndmask_b32_e64 v97, v97, v100, s[8:9]
	v_rsq_f32_e32 v97, v97
	s_nop 0
	v_mul_f32_e32 v100, 0x45800000, v97
	v_cndmask_b32_e64 v97, v97, v100, s[8:9]
	v_mul_f32_e32 v100, v110, v97
	v_mul_f32_e32 v100, v238, v100
	v_mul_f32_e32 v100, v164, v100
	v_med3_f32 v100, v100, s57, v194
	v_cvt_f16_f32_e32 v100, v100
	global_store_short v[160:161], v100, off
	v_mul_f32_e32 v100, v106, v97
	v_mul_f32_e32 v100, v237, v100
	v_mul_f32_e32 v100, v165, v100
	v_med3_f32 v100, v100, s57, v194
	v_cvt_f16_f32_e32 v100, v100
	global_store_short v[158:159], v100, off
	v_mul_f32_e32 v100, v102, v97
	v_mul_f32_e32 v97, v98, v97
	v_mul_f32_e32 v97, v235, v97
	v_mul_f32_e32 v97, v167, v97
	v_med3_f32 v97, v97, s57, v194
	v_cvt_f16_f32_e32 v97, v97
	v_mul_f32_e32 v100, v236, v100
	v_mul_f32_e32 v100, v166, v100
	v_med3_f32 v100, v100, s57, v194
	global_store_short v[154:155], v97, off
	v_mul_f32_e32 v97, 0x4b800000, v96
	v_cndmask_b32_e32 v96, v96, v97, vcc
	v_rsq_f32_e32 v96, v96
	v_cvt_f16_f32_e32 v100, v100
	v_mul_f32_e32 v97, 0x45800000, v96
	v_cndmask_b32_e32 v96, v96, v97, vcc
	v_cvt_f32_f16_e32 v97, v226
	global_store_short v[156:157], v100, off
	v_mul_f32_e32 v98, v111, v96
	v_mul_f32_e32 v98, v238, v98
	v_mul_f32_e32 v100, 0xbfb8aa3b, v97
	v_exp_f32_e32 v100, v100
	s_nop 0
	v_add_f32_e32 v100, 1.0, v100
	v_div_scale_f32 v101, s[8:9], v100, v100, v97
	v_rcp_f32_e32 v102, v101
	s_nop 0
	v_fma_f32 v104, -v101, v102, 1.0
	v_fmac_f32_e32 v102, v104, v102
	v_div_scale_f32 v104, vcc, v97, v100, v97
	v_mul_f32_e32 v105, v104, v102
	v_fma_f32 v106, -v101, v105, v104
	v_fmac_f32_e32 v105, v106, v102
	v_fma_f32 v101, -v101, v105, v104
	v_div_fmas_f32 v101, v101, v102, v105
	v_div_fixup_f32 v97, v101, v100, v97
	v_mul_f32_e32 v97, v97, v98
	v_med3_f32 v97, v97, s57, v194
	v_cvt_f16_f32_e32 v97, v97
	v_mul_f32_e32 v98, v107, v96
	v_mul_f32_e32 v98, v237, v98
	global_store_short v[152:153], v97, off
	v_cvt_f32_f16_e32 v97, v225
	v_mul_f32_e32 v100, 0xbfb8aa3b, v97
	v_exp_f32_e32 v100, v100
	s_nop 0
	v_add_f32_e32 v100, 1.0, v100
	v_div_scale_f32 v101, s[8:9], v100, v100, v97
	v_rcp_f32_e32 v102, v101
	s_nop 0
	v_fma_f32 v104, -v101, v102, 1.0
	v_fmac_f32_e32 v102, v104, v102
	v_div_scale_f32 v104, vcc, v97, v100, v97
	v_mul_f32_e32 v105, v104, v102
	v_fma_f32 v106, -v101, v105, v104
	v_fmac_f32_e32 v105, v106, v102
	v_fma_f32 v101, -v101, v105, v104
	v_div_fmas_f32 v101, v101, v102, v105
	v_div_fixup_f32 v97, v101, v100, v97
	v_mul_f32_e32 v97, v97, v98
	v_med3_f32 v97, v97, s57, v194
	v_cvt_f16_f32_e32 v97, v97
	v_mul_f32_e32 v98, v103, v96
	v_mul_f32_e32 v98, v236, v98
	v_mul_f32_e32 v96, v99, v96
	global_store_short v[150:151], v97, off
	v_cvt_f32_f16_e32 v97, v224
	v_mul_f32_e32 v96, v235, v96
	v_mul_f32_e32 v100, 0xbfb8aa3b, v97
	v_exp_f32_e32 v100, v100
	s_nop 0
	v_add_f32_e32 v100, 1.0, v100
	v_div_scale_f32 v101, s[8:9], v100, v100, v97
	v_rcp_f32_e32 v102, v101
	s_nop 0
	v_fma_f32 v103, -v101, v102, 1.0
	v_fmac_f32_e32 v102, v103, v102
	v_div_scale_f32 v103, vcc, v97, v100, v97
	v_mul_f32_e32 v104, v103, v102
	v_fma_f32 v105, -v101, v104, v103
	v_fmac_f32_e32 v104, v105, v102
	v_fma_f32 v101, -v101, v104, v103
	v_div_fmas_f32 v101, v101, v102, v104
	v_div_fixup_f32 v97, v101, v100, v97
	v_mul_f32_e32 v97, v97, v98
	v_med3_f32 v97, v97, s57, v194
	v_cvt_f16_f32_e32 v97, v97
	global_store_short v[148:149], v97, off
	v_cvt_f32_f16_e32 v97, v223
	v_mul_f32_e32 v98, 0xbfb8aa3b, v97
	v_exp_f32_e32 v98, v98
	s_nop 0
	v_add_f32_e32 v98, 1.0, v98
	v_div_scale_f32 v99, s[8:9], v98, v98, v97
	v_rcp_f32_e32 v100, v99
	s_nop 0
	v_fma_f32 v101, -v99, v100, 1.0
	v_fmac_f32_e32 v100, v101, v100
	v_div_scale_f32 v101, vcc, v97, v98, v97
	v_mul_f32_e32 v102, v101, v100
	v_fma_f32 v103, -v99, v102, v101
	v_fmac_f32_e32 v102, v103, v100
	v_fma_f32 v99, -v99, v102, v101
	v_div_fmas_f32 v99, v99, v100, v102
	v_div_fixup_f32 v97, v99, v98, v97
	v_mul_f32_e32 v96, v97, v96
	v_med3_f32 v96, v96, s57, v194
	v_cvt_f16_f32_e32 v96, v96
	s_andn2_b64 vcc, exec, s[10:11]
	global_store_short v[146:147], v96, off
	ds_read_b128 v[96:99], v116 offset:55296
	ds_read_b128 v[240:243], v117 offset:36864
	ds_read_b128 v[244:247], v117 offset:39168
	ds_read_b128 v[252:255], v117 offset:41472
	s_waitcnt lgkmcnt(2)
	v_mul_f32_e64 v82, v82, v112
	v_mul_f32_e64 v83, v83, v112
	v_mul_f32_e64 v80, v80, v112
	v_mul_f32_e64 v81, v81, v112
	v_mul_f32_e64 v86, v86, v112
	v_mul_f32_e64 v87, v87, v112
	v_mul_f32_e64 v84, v84, v112
	v_mul_f32_e64 v85, v85, v112
	v_mul_f32_e64 v90, v90, v112
	v_mul_f32_e64 v91, v91, v112
	v_mul_f32_e64 v88, v88, v112
	v_mul_f32_e64 v89, v89, v112
	v_mul_f32_e64 v94, v94, v112
	v_mul_f32_e64 v95, v95, v112
	v_mul_f32_e64 v92, v92, v112
	v_mul_f32_e64 v93, v93, v112
	s_nop 1
	v_mfma_f32_16x16x32_f16 v[80:83], v[96:99], v[240:243], v[80:83]
	ds_read_b128 v[240:243], v117 offset:43776
	ds_read_b128 v[100:103], v116 offset:55360
	s_waitcnt lgkmcnt(3)
	v_mfma_f32_16x16x32_f16 v[84:87], v[96:99], v[244:247], v[84:87]
	ds_read_b128 v[244:247], v117 offset:36928
	s_waitcnt lgkmcnt(3)
	v_mfma_f32_16x16x32_f16 v[88:91], v[96:99], v[252:255], v[88:91]
	ds_read_b128 v[252:255], v117 offset:39232
	s_waitcnt lgkmcnt(3)
	v_mfma_f32_16x16x32_f16 v[92:95], v[96:99], v[240:243], v[92:95]
	ds_read_b128 v[240:243], v117 offset:41536
	s_waitcnt lgkmcnt(2)
	v_mfma_f32_16x16x32_f16 v[80:83], v[100:103], v[244:247], v[80:83]
	ds_read_b128 v[244:247], v117 offset:43840
	s_waitcnt lgkmcnt(2)
	v_mfma_f32_16x16x32_f16 v[84:87], v[100:103], v[252:255], v[84:87]
	s_waitcnt lgkmcnt(1)
	v_mfma_f32_16x16x32_f16 v[88:91], v[100:103], v[240:243], v[88:91]
	s_waitcnt lgkmcnt(0)
	s_barrier
	v_mfma_f32_16x16x32_f16 v[92:95], v[100:103], v[244:247], v[92:95]
	v_max_f32_e32 v96, v80, v80
	v_med3_f32 v96, v96, s57, v194
	v_cvt_f16_f32_e32 v96, v96
	ds_write_b16 v215, v96 offset:46080
	v_max_f32_e32 v96, v81, v81
	v_med3_f32 v96, v96, s57, v194
	v_cvt_f16_f32_e32 v96, v96
	ds_write_b16 v215, v96 offset:46224
	v_max_f32_e32 v96, v82, v82
	v_med3_f32 v96, v96, s57, v194
	v_cvt_f16_f32_e32 v96, v96
	ds_write_b16 v215, v96 offset:46368
	v_max_f32_e32 v96, v83, v83
	v_med3_f32 v96, v96, s57, v194
	v_cvt_f16_f32_e32 v96, v96
	ds_write_b16 v215, v96 offset:46512
	v_max_f32_e32 v96, v84, v84
	v_med3_f32 v96, v96, s57, v194
	v_cvt_f16_f32_e32 v96, v96
	ds_write_b16 v215, v96 offset:46112
	v_max_f32_e32 v96, v85, v85
	v_med3_f32 v96, v96, s57, v194
	v_cvt_f16_f32_e32 v96, v96
	ds_write_b16 v216, v96 offset:46224
	v_max_f32_e32 v96, v86, v86
	v_med3_f32 v96, v96, s57, v194
	v_cvt_f16_f32_e32 v96, v96
	ds_write_b16 v216, v96 offset:46368
	v_max_f32_e32 v96, v87, v87
	v_med3_f32 v96, v96, s57, v194
	v_cvt_f16_f32_e32 v96, v96
	ds_write_b16 v216, v96 offset:46512
	v_max_f32_e32 v96, v88, v88
	v_med3_f32 v96, v96, s57, v194
	v_cvt_f16_f32_e32 v96, v96
	ds_write_b16 v215, v96 offset:46144
	v_max_f32_e32 v96, v89, v89
	v_med3_f32 v96, v96, s57, v194
	v_cvt_f16_f32_e32 v96, v96
	ds_write_b16 v217, v96 offset:46224
	v_max_f32_e32 v96, v90, v90
	v_med3_f32 v96, v96, s57, v194
	v_cvt_f16_f32_e32 v96, v96
	ds_write_b16 v217, v96 offset:46368
	v_max_f32_e32 v96, v91, v91
	v_med3_f32 v96, v96, s57, v194
	v_cvt_f16_f32_e32 v96, v96
	ds_write_b16 v217, v96 offset:46512
	v_max_f32_e32 v96, v92, v92
	v_med3_f32 v96, v96, s57, v194
	v_cvt_f16_f32_e32 v96, v96
	ds_write_b16 v215, v96 offset:46176
	v_max_f32_e32 v96, v93, v93
	v_med3_f32 v96, v96, s57, v194
	v_cvt_f16_f32_e32 v96, v96
	ds_write_b16 v218, v96 offset:46224
	v_max_f32_e32 v96, v94, v94
	v_med3_f32 v96, v96, s57, v194
	v_cvt_f16_f32_e32 v96, v96
	ds_write_b16 v218, v96 offset:46368
	v_max_f32_e32 v96, v95, v95
	v_med3_f32 v96, v96, s57, v194
	v_cvt_f16_f32_e32 v96, v96
	ds_write_b16 v218, v96 offset:46512
	s_cbranch_vccnz .LBB0_520
	ds_write_b128 v220, v[56:59]
	ds_write_b128 v211, v[60:63]
	ds_write_b128 v221, v[64:67]
	ds_write_b128 v212, v[68:71]
	ds_write_b128 v222, v[72:75]
	ds_write_b128 v213, v[76:79]
	s_branch .LBB0_520
